# merge-GEMM epilogues: gate / previous-merged operands of following steps requested ahead, counted waits
# baseline (speedup 1.0000x reference)
.LBB0_1405:
	v_lshl_or_b32 v140, s42, 8, v163
	v_lshl_add_u32 v142, s43, 8, v160
	v_ashrrev_i32_e32 v141, 31, v140
	v_mov_b64_e32 v[144:145], s[12:13]
	v_mad_i64_i32 v[166:167], s[18:19], v142, s63, v[144:145]
	v_lshlrev_b64 v[140:141], 1, v[140:141]
	v_lshl_add_u64 v[172:173], v[166:167], 0, v[140:141]
	global_load_dwordx4 v[166:169], v[172:173], off
	global_load_dwordx4 v[176:179], v[172:173], off offset:256
	v_mov_b32_e32 v165, 0x46000
	v_add_co_u32_e64 v182, s[18:19], v165, v172
	s_nop 1
	v_addc_co_u32_e64 v183, s[18:19], 0, v173, s[18:19]
	global_load_dwordx4 v[182:185], v[182:183], off
	v_mov_b32_e32 v165, 0x46000
	v_add_co_u32_e64 v186, s[18:19], v165, v172
	s_nop 1
	v_addc_co_u32_e64 v187, s[18:19], 0, v173, s[18:19]
	global_load_dwordx4 v[186:189], v[186:187], off offset:256
	v_mov_b32_e32 v165, 0x8c000
	v_add_co_u32_e64 v204, s[18:19], v165, v172
	s_nop 1
	v_addc_co_u32_e64 v205, s[18:19], 0, v173, s[18:19]
	global_load_dwordx4 v[204:207], v[204:205], off
	v_mov_b32_e32 v165, 0x8c000
	v_add_co_u32_e64 v208, s[18:19], v165, v172
	s_nop 1
	v_addc_co_u32_e64 v209, s[18:19], 0, v173, s[18:19]
	global_load_dwordx4 v[208:211], v[208:209], off offset:256
	v_mov_b32_e32 v165, 0xd2000
	v_add_co_u32_e64 v212, s[18:19], v165, v172
	s_nop 1
	v_addc_co_u32_e64 v213, s[18:19], 0, v173, s[18:19]
	global_load_dwordx4 v[212:215], v[212:213], off
	v_mov_b32_e32 v165, 0xd2000
	v_add_co_u32_e64 v216, s[18:19], v165, v172
	s_nop 1
	v_addc_co_u32_e64 v217, s[18:19], 0, v173, s[18:19]
	global_load_dwordx4 v[216:219], v[216:217], off offset:256
	v_mov_b32_e32 v165, 0x230000
	v_add_co_u32_e64 v220, s[18:19], v165, v172
	s_nop 1
	v_addc_co_u32_e64 v221, s[18:19], 0, v173, s[18:19]
	global_load_dwordx4 v[220:223], v[220:221], off
	v_mov_b32_e32 v165, 0x230000
	v_add_co_u32_e64 v224, s[18:19], v165, v172
	s_nop 1
	v_addc_co_u32_e64 v225, s[18:19], 0, v173, s[18:19]
	global_load_dwordx4 v[224:227], v[224:225], off offset:256
	v_mov_b32_e32 v165, 0x276000
	v_add_co_u32_e64 v228, s[18:19], v165, v172
	s_nop 1
	v_addc_co_u32_e64 v229, s[18:19], 0, v173, s[18:19]
	global_load_dwordx4 v[228:231], v[228:229], off
	v_mov_b32_e32 v165, 0x276000
	v_add_co_u32_e64 v232, s[18:19], v165, v172
	s_nop 1
	v_addc_co_u32_e64 v233, s[18:19], 0, v173, s[18:19]
	global_load_dwordx4 v[232:235], v[232:233], off offset:256
	v_mov_b32_e32 v165, 0x2bc000
	v_add_co_u32_e64 v236, s[18:19], v165, v172
	s_nop 1
	v_addc_co_u32_e64 v237, s[18:19], 0, v173, s[18:19]
	global_load_dwordx4 v[236:239], v[236:237], off
	v_mov_b32_e32 v165, 0x2bc000
	v_add_co_u32_e64 v240, s[18:19], v165, v172
	s_nop 1
	v_addc_co_u32_e64 v241, s[18:19], 0, v173, s[18:19]
	global_load_dwordx4 v[240:243], v[240:241], off offset:256
	v_mov_b32_e32 v165, 0x302000
	v_add_co_u32_e64 v244, s[18:19], v165, v172
	s_nop 1
	v_addc_co_u32_e64 v245, s[18:19], 0, v173, s[18:19]
	global_load_dwordx4 v[244:247], v[244:245], off
	v_ashrrev_i32_e32 v143, 31, v142
	v_lshlrev_b64 v[170:171], 11, v[142:143]
	s_and_b64 vcc, exec, s[8:9]
	s_waitcnt vmcnt(14)
	v_lshlrev_b32_e32 v174, 16, v166
	v_and_b32_e32 v175, 0xffff0000, v166
	v_lshlrev_b32_e32 v166, 16, v167
	v_and_b32_e32 v167, 0xffff0000, v167
	v_pk_mul_f32 v[128:129], v[128:129], v[166:167]
	v_lshlrev_b32_e32 v166, 16, v168
	v_and_b32_e32 v167, 0xffff0000, v168
	v_pk_mul_f32 v[166:167], v[122:123], v[166:167]
	v_lshlrev_b32_e32 v122, 16, v169
	v_and_b32_e32 v123, 0xffff0000, v169
	v_pk_mul_f32 v[126:127], v[126:127], v[174:175]
	v_pk_mul_f32 v[168:169], v[124:125], v[122:123]
	v_lshl_add_u64 v[122:123], s[4:5], 0, v[170:171]
	v_lshl_add_u64 v[170:171], v[122:123], 0, v[140:141]
	v_cvt_pk_bf16_f32 v122, v126, v127
	v_cvt_pk_bf16_f32 v123, v128, v129
	v_cvt_pk_bf16_f32 v124, v166, v167
	v_cvt_pk_bf16_f32 v125, v168, v169
	global_store_dwordx4 v[170:171], v[122:125], off
	s_waitcnt vmcnt(14)
	s_nop 1
	v_mov_b64_e32 v[122:123], v[176:177]
	v_mov_b64_e32 v[124:125], v[178:179]
	v_mov_b32_e32 v165, 0x302000
	v_add_co_u32_e64 v176, s[18:19], v165, v172
	s_nop 1
	v_addc_co_u32_e64 v177, s[18:19], 0, v173, s[18:19]
	global_load_dwordx4 v[176:179], v[176:177], off offset:256
	v_lshlrev_b32_e32 v126, 16, v122
	v_and_b32_e32 v127, 0xffff0000, v122
	v_lshlrev_b32_e32 v122, 16, v123
	v_and_b32_e32 v123, 0xffff0000, v123
	v_pk_mul_f32 v[120:121], v[120:121], v[122:123]
	v_lshlrev_b32_e32 v122, 16, v124
	v_and_b32_e32 v123, 0xffff0000, v124
	v_pk_mul_f32 v[122:123], v[114:115], v[122:123]
	v_lshlrev_b32_e32 v114, 16, v125
	v_and_b32_e32 v115, 0xffff0000, v125
	v_pk_mul_f32 v[118:119], v[118:119], v[126:127]
	v_pk_mul_f32 v[124:125], v[116:117], v[114:115]
	v_cvt_pk_bf16_f32 v114, v118, v119
	v_cvt_pk_bf16_f32 v115, v120, v121
	v_cvt_pk_bf16_f32 v116, v122, v123
	v_cvt_pk_bf16_f32 v117, v124, v125
	global_store_dwordx4 v[170:171], v[114:117], off offset:256
	s_nop 1
	v_or_b32_e32 v114, 16, v142
	v_ashrrev_i32_e32 v115, 31, v114
	v_lshlrev_b64 v[120:121], 11, v[114:115]
	v_mad_i64_i32 v[114:115], s[18:19], v114, s63, v[144:145]
	v_lshl_add_u64 v[114:115], v[114:115], 0, v[140:141]
	s_waitcnt vmcnt(15)
	s_nop 1
	v_mov_b64_e32 v[116:117], v[182:183]
	v_mov_b64_e32 v[118:119], v[184:185]
	v_lshlrev_b32_e32 v122, 16, v116
	v_and_b32_e32 v123, 0xffff0000, v116
	v_lshlrev_b32_e32 v116, 16, v117
	v_and_b32_e32 v117, 0xffff0000, v117
	v_pk_mul_f32 v[112:113], v[112:113], v[116:117]
	v_lshlrev_b32_e32 v116, 16, v118
	v_and_b32_e32 v117, 0xffff0000, v118
	v_pk_mul_f32 v[116:117], v[106:107], v[116:117]
	v_lshlrev_b32_e32 v106, 16, v119
	v_and_b32_e32 v107, 0xffff0000, v119
	v_pk_mul_f32 v[110:111], v[110:111], v[122:123]
	v_pk_mul_f32 v[118:119], v[108:109], v[106:107]
	v_lshl_add_u64 v[106:107], s[4:5], 0, v[120:121]
	v_lshl_add_u64 v[120:121], v[106:107], 0, v[140:141]
	v_cvt_pk_bf16_f32 v106, v110, v111
	v_cvt_pk_bf16_f32 v107, v112, v113
	v_cvt_pk_bf16_f32 v108, v116, v117
	v_cvt_pk_bf16_f32 v109, v118, v119
	global_store_dwordx4 v[120:121], v[106:109], off
	s_waitcnt vmcnt(15)
	s_nop 1
	v_mov_b64_e32 v[106:107], v[186:187]
	v_mov_b64_e32 v[108:109], v[188:189]
	v_lshlrev_b32_e32 v110, 16, v106
	v_and_b32_e32 v111, 0xffff0000, v106
	v_lshlrev_b32_e32 v106, 16, v107
	v_and_b32_e32 v107, 0xffff0000, v107
	v_pk_mul_f32 v[104:105], v[104:105], v[106:107]
	v_lshlrev_b32_e32 v106, 16, v108
	v_and_b32_e32 v107, 0xffff0000, v108
	v_pk_mul_f32 v[106:107], v[98:99], v[106:107]
	v_lshlrev_b32_e32 v98, 16, v109
	v_and_b32_e32 v99, 0xffff0000, v109
	v_pk_mul_f32 v[102:103], v[102:103], v[110:111]
	v_pk_mul_f32 v[108:109], v[100:101], v[98:99]
	v_cvt_pk_bf16_f32 v98, v102, v103
	v_cvt_pk_bf16_f32 v99, v104, v105
	v_cvt_pk_bf16_f32 v100, v106, v107
	v_cvt_pk_bf16_f32 v101, v108, v109
	global_store_dwordx4 v[120:121], v[98:101], off offset:256
	s_nop 1
	v_or_b32_e32 v98, 32, v142
	v_ashrrev_i32_e32 v99, 31, v98
	v_lshlrev_b64 v[104:105], 11, v[98:99]
	v_mad_i64_i32 v[98:99], s[18:19], v98, s63, v[144:145]
	v_lshl_add_u64 v[98:99], v[98:99], 0, v[140:141]
	s_waitcnt vmcnt(15)
	s_nop 1
	v_mov_b64_e32 v[100:101], v[204:205]
	v_mov_b64_e32 v[102:103], v[206:207]
	v_lshlrev_b32_e32 v106, 16, v100
	v_and_b32_e32 v107, 0xffff0000, v100
	v_lshlrev_b32_e32 v100, 16, v101
	v_and_b32_e32 v101, 0xffff0000, v101
	v_pk_mul_f32 v[96:97], v[96:97], v[100:101]
	v_lshlrev_b32_e32 v100, 16, v102
	v_and_b32_e32 v101, 0xffff0000, v102
	v_pk_mul_f32 v[100:101], v[90:91], v[100:101]
	v_lshlrev_b32_e32 v90, 16, v103
	v_and_b32_e32 v91, 0xffff0000, v103
	v_pk_mul_f32 v[94:95], v[94:95], v[106:107]
	v_pk_mul_f32 v[102:103], v[92:93], v[90:91]
	v_lshl_add_u64 v[90:91], s[4:5], 0, v[104:105]
	v_lshl_add_u64 v[104:105], v[90:91], 0, v[140:141]
	v_cvt_pk_bf16_f32 v90, v94, v95
	v_cvt_pk_bf16_f32 v91, v96, v97
	v_cvt_pk_bf16_f32 v92, v100, v101
	v_cvt_pk_bf16_f32 v93, v102, v103
	global_store_dwordx4 v[104:105], v[90:93], off
	s_waitcnt vmcnt(15)
	s_nop 1
	v_mov_b64_e32 v[90:91], v[208:209]
	v_mov_b64_e32 v[92:93], v[210:211]
	v_lshlrev_b32_e32 v94, 16, v90
	v_and_b32_e32 v95, 0xffff0000, v90
	v_lshlrev_b32_e32 v90, 16, v91
	v_and_b32_e32 v91, 0xffff0000, v91
	v_pk_mul_f32 v[88:89], v[88:89], v[90:91]
	v_lshlrev_b32_e32 v90, 16, v92
	v_and_b32_e32 v91, 0xffff0000, v92
	v_pk_mul_f32 v[90:91], v[82:83], v[90:91]
	v_lshlrev_b32_e32 v82, 16, v93
	v_and_b32_e32 v83, 0xffff0000, v93
	v_pk_mul_f32 v[86:87], v[86:87], v[94:95]
	v_pk_mul_f32 v[92:93], v[84:85], v[82:83]
	v_cvt_pk_bf16_f32 v82, v86, v87
	v_cvt_pk_bf16_f32 v83, v88, v89
	v_cvt_pk_bf16_f32 v84, v90, v91
	v_cvt_pk_bf16_f32 v85, v92, v93
	global_store_dwordx4 v[104:105], v[82:85], off offset:256
	s_nop 1
	v_or_b32_e32 v82, 48, v142
	v_ashrrev_i32_e32 v83, 31, v82
	v_lshlrev_b64 v[88:89], 11, v[82:83]
	v_mad_i64_i32 v[82:83], s[18:19], v82, s63, v[144:145]
	v_lshl_add_u64 v[82:83], v[82:83], 0, v[140:141]
	s_waitcnt vmcnt(15)
	s_nop 1
	v_mov_b64_e32 v[84:85], v[212:213]
	v_mov_b64_e32 v[86:87], v[214:215]
	v_lshlrev_b32_e32 v90, 16, v84
	v_and_b32_e32 v91, 0xffff0000, v84
	v_lshlrev_b32_e32 v84, 16, v85
	v_and_b32_e32 v85, 0xffff0000, v85
	v_pk_mul_f32 v[80:81], v[80:81], v[84:85]
	v_lshlrev_b32_e32 v84, 16, v86
	v_and_b32_e32 v85, 0xffff0000, v86
	v_pk_mul_f32 v[84:85], v[74:75], v[84:85]
	v_lshlrev_b32_e32 v74, 16, v87
	v_and_b32_e32 v75, 0xffff0000, v87
	v_pk_mul_f32 v[78:79], v[78:79], v[90:91]
	v_pk_mul_f32 v[86:87], v[76:77], v[74:75]
	v_lshl_add_u64 v[74:75], s[4:5], 0, v[88:89]
	v_lshl_add_u64 v[88:89], v[74:75], 0, v[140:141]
	v_cvt_pk_bf16_f32 v74, v78, v79
	v_cvt_pk_bf16_f32 v75, v80, v81
	v_cvt_pk_bf16_f32 v76, v84, v85
	v_cvt_pk_bf16_f32 v77, v86, v87
	global_store_dwordx4 v[88:89], v[74:77], off
	s_waitcnt vmcnt(15)
	s_nop 1
	v_mov_b64_e32 v[74:75], v[216:217]
	v_mov_b64_e32 v[76:77], v[218:219]
	v_lshlrev_b32_e32 v78, 16, v74
	v_and_b32_e32 v79, 0xffff0000, v74
	v_lshlrev_b32_e32 v74, 16, v75
	v_and_b32_e32 v75, 0xffff0000, v75
	v_pk_mul_f32 v[72:73], v[72:73], v[74:75]
	v_lshlrev_b32_e32 v74, 16, v76
	v_and_b32_e32 v75, 0xffff0000, v76
	v_pk_mul_f32 v[74:75], v[66:67], v[74:75]
	v_lshlrev_b32_e32 v66, 16, v77
	v_and_b32_e32 v67, 0xffff0000, v77
	v_pk_mul_f32 v[70:71], v[70:71], v[78:79]
	v_pk_mul_f32 v[76:77], v[68:69], v[66:67]
	v_cvt_pk_bf16_f32 v66, v70, v71
	v_cvt_pk_bf16_f32 v67, v72, v73
	v_cvt_pk_bf16_f32 v68, v74, v75
	v_cvt_pk_bf16_f32 v69, v76, v77
	global_store_dwordx4 v[88:89], v[66:69], off offset:256
	s_nop 1
	v_add_u32_e32 v66, 0x80, v142
	v_ashrrev_i32_e32 v67, 31, v66
	v_lshlrev_b64 v[72:73], 11, v[66:67]
	v_mad_i64_i32 v[66:67], s[18:19], v66, s63, v[144:145]
	v_lshl_add_u64 v[66:67], v[66:67], 0, v[140:141]
	s_waitcnt vmcnt(15)
	s_nop 1
	v_mov_b64_e32 v[68:69], v[220:221]
	v_mov_b64_e32 v[70:71], v[222:223]
	v_lshlrev_b32_e32 v74, 16, v68
	v_and_b32_e32 v75, 0xffff0000, v68
	v_lshlrev_b32_e32 v68, 16, v69
	v_and_b32_e32 v69, 0xffff0000, v69
	v_pk_mul_f32 v[64:65], v[64:65], v[68:69]
	v_lshlrev_b32_e32 v68, 16, v70
	v_and_b32_e32 v69, 0xffff0000, v70
	v_pk_mul_f32 v[68:69], v[58:59], v[68:69]
	v_lshlrev_b32_e32 v58, 16, v71
	v_and_b32_e32 v59, 0xffff0000, v71
	v_pk_mul_f32 v[62:63], v[62:63], v[74:75]
	v_pk_mul_f32 v[70:71], v[60:61], v[58:59]
	v_lshl_add_u64 v[58:59], s[4:5], 0, v[72:73]
	v_lshl_add_u64 v[72:73], v[58:59], 0, v[140:141]
	v_cvt_pk_bf16_f32 v58, v62, v63
	v_cvt_pk_bf16_f32 v59, v64, v65
	v_cvt_pk_bf16_f32 v60, v68, v69
	v_cvt_pk_bf16_f32 v61, v70, v71
	global_store_dwordx4 v[72:73], v[58:61], off
	s_waitcnt vmcnt(15)
	s_nop 1
	v_mov_b64_e32 v[58:59], v[224:225]
	v_mov_b64_e32 v[60:61], v[226:227]
	v_lshlrev_b32_e32 v62, 16, v58
	v_and_b32_e32 v63, 0xffff0000, v58
	v_lshlrev_b32_e32 v58, 16, v59
	v_and_b32_e32 v59, 0xffff0000, v59
	v_pk_mul_f32 v[56:57], v[56:57], v[58:59]
	v_lshlrev_b32_e32 v58, 16, v60
	v_and_b32_e32 v59, 0xffff0000, v60
	v_pk_mul_f32 v[58:59], v[50:51], v[58:59]
	v_lshlrev_b32_e32 v50, 16, v61
	v_and_b32_e32 v51, 0xffff0000, v61
	v_pk_mul_f32 v[54:55], v[54:55], v[62:63]
	v_pk_mul_f32 v[60:61], v[52:53], v[50:51]
	v_cvt_pk_bf16_f32 v50, v54, v55
	v_cvt_pk_bf16_f32 v51, v56, v57
	v_cvt_pk_bf16_f32 v52, v58, v59
	v_cvt_pk_bf16_f32 v53, v60, v61
	global_store_dwordx4 v[72:73], v[50:53], off offset:256
	s_nop 1
	v_add_u32_e32 v50, 0x90, v142
	v_ashrrev_i32_e32 v51, 31, v50
	v_lshlrev_b64 v[56:57], 11, v[50:51]
	v_mad_i64_i32 v[50:51], s[18:19], v50, s63, v[144:145]
	v_lshl_add_u64 v[50:51], v[50:51], 0, v[140:141]
	s_waitcnt vmcnt(15)
	s_nop 1
	v_mov_b64_e32 v[52:53], v[228:229]
	v_mov_b64_e32 v[54:55], v[230:231]
	v_lshlrev_b32_e32 v58, 16, v52
	v_and_b32_e32 v59, 0xffff0000, v52
	v_lshlrev_b32_e32 v52, 16, v53
	v_and_b32_e32 v53, 0xffff0000, v53
	v_pk_mul_f32 v[48:49], v[48:49], v[52:53]
	v_lshlrev_b32_e32 v52, 16, v54
	v_and_b32_e32 v53, 0xffff0000, v54
	v_pk_mul_f32 v[52:53], v[42:43], v[52:53]
	v_lshlrev_b32_e32 v42, 16, v55
	v_and_b32_e32 v43, 0xffff0000, v55
	v_pk_mul_f32 v[46:47], v[46:47], v[58:59]
	v_pk_mul_f32 v[54:55], v[44:45], v[42:43]
	v_lshl_add_u64 v[42:43], s[4:5], 0, v[56:57]
	v_lshl_add_u64 v[56:57], v[42:43], 0, v[140:141]
	v_cvt_pk_bf16_f32 v42, v46, v47
	v_cvt_pk_bf16_f32 v43, v48, v49
	v_cvt_pk_bf16_f32 v44, v52, v53
	v_cvt_pk_bf16_f32 v45, v54, v55
	global_store_dwordx4 v[56:57], v[42:45], off
	s_waitcnt vmcnt(15)
	s_nop 1
	v_mov_b64_e32 v[42:43], v[232:233]
	v_mov_b64_e32 v[44:45], v[234:235]
	v_lshlrev_b32_e32 v46, 16, v42
	v_and_b32_e32 v47, 0xffff0000, v42
	v_lshlrev_b32_e32 v42, 16, v43
	v_and_b32_e32 v43, 0xffff0000, v43
	v_pk_mul_f32 v[40:41], v[40:41], v[42:43]
	v_lshlrev_b32_e32 v42, 16, v44
	v_and_b32_e32 v43, 0xffff0000, v44
	v_pk_mul_f32 v[42:43], v[34:35], v[42:43]
	v_lshlrev_b32_e32 v34, 16, v45
	v_and_b32_e32 v35, 0xffff0000, v45
	v_pk_mul_f32 v[38:39], v[38:39], v[46:47]
	v_pk_mul_f32 v[44:45], v[36:37], v[34:35]
	v_cvt_pk_bf16_f32 v34, v38, v39
	v_cvt_pk_bf16_f32 v35, v40, v41
	v_cvt_pk_bf16_f32 v36, v42, v43
	v_cvt_pk_bf16_f32 v37, v44, v45
	global_store_dwordx4 v[56:57], v[34:37], off offset:256
	s_nop 1
	v_add_u32_e32 v34, 0xa0, v142
	v_ashrrev_i32_e32 v35, 31, v34
	v_lshlrev_b64 v[40:41], 11, v[34:35]
	v_mad_i64_i32 v[34:35], s[18:19], v34, s63, v[144:145]
	v_lshl_add_u64 v[34:35], v[34:35], 0, v[140:141]
	s_waitcnt vmcnt(15)
	s_nop 1
	v_mov_b64_e32 v[36:37], v[236:237]
	v_mov_b64_e32 v[38:39], v[238:239]
	v_lshlrev_b32_e32 v42, 16, v36
	v_and_b32_e32 v43, 0xffff0000, v36
	v_lshlrev_b32_e32 v36, 16, v37
	v_and_b32_e32 v37, 0xffff0000, v37
	v_pk_mul_f32 v[32:33], v[32:33], v[36:37]
	v_lshlrev_b32_e32 v36, 16, v38
	v_and_b32_e32 v37, 0xffff0000, v38
	v_pk_mul_f32 v[36:37], v[26:27], v[36:37]
	v_lshlrev_b32_e32 v26, 16, v39
	v_and_b32_e32 v27, 0xffff0000, v39
	v_pk_mul_f32 v[30:31], v[30:31], v[42:43]
	v_pk_mul_f32 v[38:39], v[28:29], v[26:27]
	v_lshl_add_u64 v[26:27], s[4:5], 0, v[40:41]
	v_lshl_add_u64 v[40:41], v[26:27], 0, v[140:141]
	v_cvt_pk_bf16_f32 v26, v30, v31
	v_cvt_pk_bf16_f32 v27, v32, v33
	v_cvt_pk_bf16_f32 v28, v36, v37
	v_cvt_pk_bf16_f32 v29, v38, v39
	global_store_dwordx4 v[40:41], v[26:29], off
	s_waitcnt vmcnt(15)
	s_nop 1
	v_mov_b64_e32 v[26:27], v[240:241]
	v_mov_b64_e32 v[28:29], v[242:243]
	v_lshlrev_b32_e32 v30, 16, v26
	v_and_b32_e32 v31, 0xffff0000, v26
	v_lshlrev_b32_e32 v26, 16, v27
	v_and_b32_e32 v27, 0xffff0000, v27
	v_pk_mul_f32 v[24:25], v[24:25], v[26:27]
	v_lshlrev_b32_e32 v26, 16, v28
	v_and_b32_e32 v27, 0xffff0000, v28
	v_pk_mul_f32 v[26:27], v[18:19], v[26:27]
	v_lshlrev_b32_e32 v18, 16, v29
	v_and_b32_e32 v19, 0xffff0000, v29
	v_pk_mul_f32 v[22:23], v[22:23], v[30:31]
	v_pk_mul_f32 v[28:29], v[20:21], v[18:19]
	v_cvt_pk_bf16_f32 v18, v22, v23
	v_cvt_pk_bf16_f32 v19, v24, v25
	v_cvt_pk_bf16_f32 v20, v26, v27
	v_cvt_pk_bf16_f32 v21, v28, v29
	global_store_dwordx4 v[40:41], v[18:21], off offset:256
	s_nop 1
	v_add_u32_e32 v18, 0xb0, v142
	v_ashrrev_i32_e32 v19, 31, v18
	v_lshlrev_b64 v[24:25], 11, v[18:19]
	v_mad_i64_i32 v[18:19], s[18:19], v18, s63, v[144:145]
	v_lshl_add_u64 v[18:19], v[18:19], 0, v[140:141]
	s_waitcnt vmcnt(15)
	s_nop 1
	v_mov_b64_e32 v[20:21], v[244:245]
	v_mov_b64_e32 v[22:23], v[246:247]
	s_mov_b64 s[18:19], -1
	v_lshlrev_b32_e32 v26, 16, v20
	v_and_b32_e32 v27, 0xffff0000, v20
	v_lshlrev_b32_e32 v20, 16, v21
	v_and_b32_e32 v21, 0xffff0000, v21
	v_pk_mul_f32 v[16:17], v[16:17], v[20:21]
	v_lshlrev_b32_e32 v20, 16, v22
	v_and_b32_e32 v21, 0xffff0000, v22
	v_pk_mul_f32 v[20:21], v[10:11], v[20:21]
	v_lshlrev_b32_e32 v10, 16, v23
	v_and_b32_e32 v11, 0xffff0000, v23
	v_pk_mul_f32 v[14:15], v[14:15], v[26:27]
	v_pk_mul_f32 v[22:23], v[12:13], v[10:11]
	v_lshl_add_u64 v[10:11], s[4:5], 0, v[24:25]
	v_lshl_add_u64 v[24:25], v[10:11], 0, v[140:141]
	v_cvt_pk_bf16_f32 v10, v14, v15
	v_cvt_pk_bf16_f32 v11, v16, v17
	v_cvt_pk_bf16_f32 v12, v20, v21
	v_cvt_pk_bf16_f32 v13, v22, v23
	global_store_dwordx4 v[24:25], v[10:13], off
	s_waitcnt vmcnt(14)
	s_nop 1
	v_mov_b64_e32 v[10:11], v[176:177]
	v_mov_b64_e32 v[12:13], v[178:179]
	v_lshlrev_b32_e32 v14, 16, v10
	v_and_b32_e32 v15, 0xffff0000, v10
	v_lshlrev_b32_e32 v10, 16, v11
	v_and_b32_e32 v11, 0xffff0000, v11
	v_pk_mul_f32 v[8:9], v[8:9], v[10:11]
	v_lshlrev_b32_e32 v10, 16, v12
	v_and_b32_e32 v11, 0xffff0000, v12
	v_pk_mul_f32 v[10:11], v[2:3], v[10:11]
	v_lshlrev_b32_e32 v2, 16, v13
	v_and_b32_e32 v3, 0xffff0000, v13
	v_pk_mul_f32 v[6:7], v[6:7], v[14:15]
	v_pk_mul_f32 v[12:13], v[4:5], v[2:3]
	v_cvt_pk_bf16_f32 v2, v6, v7
	v_cvt_pk_bf16_f32 v3, v8, v9
	v_cvt_pk_bf16_f32 v4, v10, v11
	v_cvt_pk_bf16_f32 v5, v12, v13
	global_store_dwordx4 v[24:25], v[2:5], off offset:256
	s_cbranch_vccnz .LBB0_1390
	s_andn2_b64 vcc, exec, s[6:7]
	s_cbranch_vccnz .LBB0_1389
	s_barrier
	s_branch .LBB0_1389

.LBB0_1429:
	v_lshl_add_u32 v142, s43, 8, v160
	v_lshl_or_b32 v140, s42, 8, v163
	v_ashrrev_i32_e32 v143, 31, v142
	v_ashrrev_i32_e32 v141, 31, v140
	v_lshlrev_b64 v[170:171], 11, v[142:143]
	v_mov_b64_e32 v[144:145], s[12:13]
	v_mad_i64_i32 v[166:167], s[18:19], v142, s63, v[144:145]
	v_lshlrev_b64 v[140:141], 1, v[140:141]
	v_lshl_add_u64 v[170:171], s[4:5], 0, v[170:171]
	v_lshl_add_u64 v[174:175], v[166:167], 0, v[140:141]
	v_lshl_add_u64 v[176:177], v[170:171], 0, v[140:141]
	global_load_dwordx4 v[166:169], v[174:175], off
	global_load_dwordx4 v[170:173], v[176:177], off
	global_load_dwordx4 v[184:187], v[174:175], off offset:256
	global_load_dwordx4 v[188:191], v[176:177], off offset:256
	v_mov_b32_e32 v165, 0x46000
	v_add_co_u32_e64 v204, s[18:19], v165, v174
	s_nop 1
	v_addc_co_u32_e64 v205, s[18:19], 0, v175, s[18:19]
	global_load_dwordx4 v[204:207], v[204:205], off
	v_mov_b32_e32 v165, 0x8000
	v_add_co_u32_e64 v208, s[18:19], v165, v176
	s_nop 1
	v_addc_co_u32_e64 v209, s[18:19], 0, v177, s[18:19]
	global_load_dwordx4 v[208:211], v[208:209], off
	v_mov_b32_e32 v165, 0x46000
	v_add_co_u32_e64 v212, s[18:19], v165, v174
	s_nop 1
	v_addc_co_u32_e64 v213, s[18:19], 0, v175, s[18:19]
	global_load_dwordx4 v[212:215], v[212:213], off offset:256
	v_mov_b32_e32 v165, 0x8000
	v_add_co_u32_e64 v216, s[18:19], v165, v176
	s_nop 1
	v_addc_co_u32_e64 v217, s[18:19], 0, v177, s[18:19]
	global_load_dwordx4 v[216:219], v[216:217], off offset:256
	v_mov_b32_e32 v165, 0x8c000
	v_add_co_u32_e64 v220, s[18:19], v165, v174
	s_nop 1
	v_addc_co_u32_e64 v221, s[18:19], 0, v175, s[18:19]
	global_load_dwordx4 v[220:223], v[220:221], off
	v_mov_b32_e32 v165, 0x10000
	v_add_co_u32_e64 v224, s[18:19], v165, v176
	s_nop 1
	v_addc_co_u32_e64 v225, s[18:19], 0, v177, s[18:19]
	global_load_dwordx4 v[224:227], v[224:225], off
	v_mov_b32_e32 v165, 0x8c000
	v_add_co_u32_e64 v228, s[18:19], v165, v174
	s_nop 1
	v_addc_co_u32_e64 v229, s[18:19], 0, v175, s[18:19]
	global_load_dwordx4 v[228:231], v[228:229], off offset:256
	v_mov_b32_e32 v165, 0x10000
	v_add_co_u32_e64 v232, s[18:19], v165, v176
	s_nop 1
	v_addc_co_u32_e64 v233, s[18:19], 0, v177, s[18:19]
	global_load_dwordx4 v[232:235], v[232:233], off offset:256
	v_mov_b32_e32 v165, 0xd2000
	v_add_co_u32_e64 v236, s[18:19], v165, v174
	s_nop 1
	v_addc_co_u32_e64 v237, s[18:19], 0, v175, s[18:19]
	global_load_dwordx4 v[236:239], v[236:237], off
	v_mov_b32_e32 v165, 0x18000
	v_add_co_u32_e64 v240, s[18:19], v165, v176
	s_nop 1
	v_addc_co_u32_e64 v241, s[18:19], 0, v177, s[18:19]
	global_load_dwordx4 v[240:243], v[240:241], off
	s_and_b64 vcc, exec, s[8:9]
	s_waitcnt vmcnt(12)
	v_lshlrev_b32_e32 v178, 16, v166
	v_and_b32_e32 v179, 0xffff0000, v166
	v_lshlrev_b32_e32 v182, 16, v170
	v_and_b32_e32 v183, 0xffff0000, v170
	v_lshlrev_b32_e32 v166, 16, v167
	v_and_b32_e32 v167, 0xffff0000, v167
	v_lshlrev_b32_e32 v170, 16, v171
	v_and_b32_e32 v171, 0xffff0000, v171
	v_pk_fma_f32 v[128:129], v[128:129], v[166:167], v[170:171]
	v_lshlrev_b32_e32 v166, 16, v168
	v_and_b32_e32 v167, 0xffff0000, v168
	v_lshlrev_b32_e32 v170, 16, v172
	v_and_b32_e32 v171, 0xffff0000, v172
	v_pk_fma_f32 v[166:167], v[122:123], v[166:167], v[170:171]
	v_lshlrev_b32_e32 v122, 16, v169
	v_and_b32_e32 v123, 0xffff0000, v169
	v_lshlrev_b32_e32 v168, 16, v173
	v_and_b32_e32 v169, 0xffff0000, v173
	v_pk_fma_f32 v[126:127], v[126:127], v[178:179], v[182:183]
	v_pk_fma_f32 v[168:169], v[124:125], v[122:123], v[168:169]
	v_cvt_pk_bf16_f32 v122, v126, v127
	v_cvt_pk_bf16_f32 v123, v128, v129
	v_cvt_pk_bf16_f32 v124, v166, v167
	v_cvt_pk_bf16_f32 v125, v168, v169
	global_store_dwordx4 v[176:177], v[122:125], off
	s_waitcnt vmcnt(12)
	s_nop 1
	v_mov_b64_e32 v[122:123], v[184:185]
	v_mov_b64_e32 v[124:125], v[186:187]
	s_nop 0
	s_waitcnt vmcnt(11)
	s_nop 1
	v_mov_b64_e32 v[126:127], v[188:189]
	v_mov_b64_e32 v[128:129], v[190:191]
	v_mov_b32_e32 v165, 0xd2000
	v_add_co_u32_e64 v184, s[18:19], v165, v174
	s_nop 1
	v_addc_co_u32_e64 v185, s[18:19], 0, v175, s[18:19]
	global_load_dwordx4 v[184:187], v[184:185], off offset:256
	v_mov_b32_e32 v165, 0x18000
	v_add_co_u32_e64 v188, s[18:19], v165, v176
	s_nop 1
	v_addc_co_u32_e64 v189, s[18:19], 0, v177, s[18:19]
	global_load_dwordx4 v[188:191], v[188:189], off offset:256
	v_lshlrev_b32_e32 v166, 16, v122
	v_and_b32_e32 v167, 0xffff0000, v122
	v_lshlrev_b32_e32 v168, 16, v126
	v_and_b32_e32 v169, 0xffff0000, v126
	v_lshlrev_b32_e32 v122, 16, v123
	v_and_b32_e32 v123, 0xffff0000, v123
	v_lshlrev_b32_e32 v126, 16, v127
	v_and_b32_e32 v127, 0xffff0000, v127
	v_pk_fma_f32 v[120:121], v[120:121], v[122:123], v[126:127]
	v_lshlrev_b32_e32 v122, 16, v124
	v_and_b32_e32 v123, 0xffff0000, v124
	v_lshlrev_b32_e32 v126, 16, v128
	v_and_b32_e32 v127, 0xffff0000, v128
	v_pk_fma_f32 v[122:123], v[114:115], v[122:123], v[126:127]
	v_lshlrev_b32_e32 v114, 16, v125
	v_and_b32_e32 v115, 0xffff0000, v125
	v_lshlrev_b32_e32 v124, 16, v129
	v_and_b32_e32 v125, 0xffff0000, v129
	v_pk_fma_f32 v[118:119], v[118:119], v[166:167], v[168:169]
	v_pk_fma_f32 v[124:125], v[116:117], v[114:115], v[124:125]
	v_cvt_pk_bf16_f32 v114, v118, v119
	v_cvt_pk_bf16_f32 v115, v120, v121
	v_cvt_pk_bf16_f32 v116, v122, v123
	v_cvt_pk_bf16_f32 v117, v124, v125
	global_store_dwordx4 v[176:177], v[114:117], off offset:256
	s_nop 1
	v_or_b32_e32 v114, 16, v142
	v_ashrrev_i32_e32 v115, 31, v114
	v_lshlrev_b64 v[120:121], 11, v[114:115]
	v_mad_i64_i32 v[114:115], s[18:19], v114, s63, v[144:145]
	v_lshl_add_u64 v[124:125], v[114:115], 0, v[140:141]
	v_lshl_add_u64 v[114:115], s[4:5], 0, v[120:121]
	v_lshl_add_u64 v[114:115], v[114:115], 0, v[140:141]
	s_waitcnt vmcnt(13)
	s_nop 1
	v_mov_b64_e32 v[116:117], v[204:205]
	v_mov_b64_e32 v[118:119], v[206:207]
	s_waitcnt vmcnt(12)
	s_nop 1
	v_mov_b64_e32 v[120:121], v[208:209]
	v_mov_b64_e32 v[122:123], v[210:211]
	v_mov_b32_e32 v165, 0x230000
	v_add_co_u32_e64 v204, s[18:19], v165, v174
	s_nop 1
	v_addc_co_u32_e64 v205, s[18:19], 0, v175, s[18:19]
	global_load_dwordx4 v[204:207], v[204:205], off
	v_mov_b32_e32 v165, 0x40000
	v_add_co_u32_e64 v208, s[18:19], v165, v176
	s_nop 1
	v_addc_co_u32_e64 v209, s[18:19], 0, v177, s[18:19]
	global_load_dwordx4 v[208:211], v[208:209], off
	v_lshlrev_b32_e32 v126, 16, v116
	v_and_b32_e32 v127, 0xffff0000, v116
	v_lshlrev_b32_e32 v128, 16, v120
	v_and_b32_e32 v129, 0xffff0000, v120
	v_lshlrev_b32_e32 v116, 16, v117
	v_and_b32_e32 v117, 0xffff0000, v117
	v_lshlrev_b32_e32 v120, 16, v121
	v_and_b32_e32 v121, 0xffff0000, v121
	v_pk_fma_f32 v[112:113], v[112:113], v[116:117], v[120:121]
	v_lshlrev_b32_e32 v116, 16, v118
	v_and_b32_e32 v117, 0xffff0000, v118
	v_lshlrev_b32_e32 v120, 16, v122
	v_and_b32_e32 v121, 0xffff0000, v122
	v_pk_fma_f32 v[116:117], v[106:107], v[116:117], v[120:121]
	v_lshlrev_b32_e32 v106, 16, v119
	v_and_b32_e32 v107, 0xffff0000, v119
	v_lshlrev_b32_e32 v118, 16, v123
	v_and_b32_e32 v119, 0xffff0000, v123
	v_pk_fma_f32 v[110:111], v[110:111], v[126:127], v[128:129]
	v_pk_fma_f32 v[118:119], v[108:109], v[106:107], v[118:119]
	v_cvt_pk_bf16_f32 v106, v110, v111
	v_cvt_pk_bf16_f32 v107, v112, v113
	v_cvt_pk_bf16_f32 v108, v116, v117
	v_cvt_pk_bf16_f32 v109, v118, v119
	global_store_dwordx4 v[114:115], v[106:109], off
	s_waitcnt vmcnt(14)
	s_nop 1
	v_mov_b64_e32 v[106:107], v[212:213]
	v_mov_b64_e32 v[108:109], v[214:215]
	s_nop 0
	s_waitcnt vmcnt(13)
	s_nop 1
	v_mov_b64_e32 v[110:111], v[216:217]
	v_mov_b64_e32 v[112:113], v[218:219]
	v_mov_b32_e32 v165, 0x230000
	v_add_co_u32_e64 v212, s[18:19], v165, v174
	s_nop 1
	v_addc_co_u32_e64 v213, s[18:19], 0, v175, s[18:19]
	global_load_dwordx4 v[212:215], v[212:213], off offset:256
	v_mov_b32_e32 v165, 0x40000
	v_add_co_u32_e64 v216, s[18:19], v165, v176
	s_nop 1
	v_addc_co_u32_e64 v217, s[18:19], 0, v177, s[18:19]
	global_load_dwordx4 v[216:219], v[216:217], off offset:256
	v_lshlrev_b32_e32 v116, 16, v106
	v_and_b32_e32 v117, 0xffff0000, v106
	v_lshlrev_b32_e32 v118, 16, v110
	v_and_b32_e32 v119, 0xffff0000, v110
	v_lshlrev_b32_e32 v106, 16, v107
	v_and_b32_e32 v107, 0xffff0000, v107
	v_lshlrev_b32_e32 v110, 16, v111
	v_and_b32_e32 v111, 0xffff0000, v111
	v_pk_fma_f32 v[104:105], v[104:105], v[106:107], v[110:111]
	v_lshlrev_b32_e32 v106, 16, v108
	v_and_b32_e32 v107, 0xffff0000, v108
	v_lshlrev_b32_e32 v110, 16, v112
	v_and_b32_e32 v111, 0xffff0000, v112
	v_pk_fma_f32 v[106:107], v[98:99], v[106:107], v[110:111]
	v_lshlrev_b32_e32 v98, 16, v109
	v_and_b32_e32 v99, 0xffff0000, v109
	v_lshlrev_b32_e32 v108, 16, v113
	v_and_b32_e32 v109, 0xffff0000, v113
	v_pk_fma_f32 v[102:103], v[102:103], v[116:117], v[118:119]
	v_pk_fma_f32 v[108:109], v[100:101], v[98:99], v[108:109]
	v_cvt_pk_bf16_f32 v98, v102, v103
	v_cvt_pk_bf16_f32 v99, v104, v105
	v_cvt_pk_bf16_f32 v100, v106, v107
	v_cvt_pk_bf16_f32 v101, v108, v109
	global_store_dwordx4 v[114:115], v[98:101], off offset:256
	s_nop 1
	v_or_b32_e32 v98, 32, v142
	v_ashrrev_i32_e32 v99, 31, v98
	v_lshlrev_b64 v[104:105], 11, v[98:99]
	v_mad_i64_i32 v[98:99], s[18:19], v98, s63, v[144:145]
	v_lshl_add_u64 v[108:109], v[98:99], 0, v[140:141]
	v_lshl_add_u64 v[98:99], s[4:5], 0, v[104:105]
	v_lshl_add_u64 v[98:99], v[98:99], 0, v[140:141]
	s_waitcnt vmcnt(15)
	s_nop 1
	v_mov_b64_e32 v[100:101], v[220:221]
	v_mov_b64_e32 v[102:103], v[222:223]
	s_waitcnt vmcnt(14)
	s_nop 1
	v_mov_b64_e32 v[104:105], v[224:225]
	v_mov_b64_e32 v[106:107], v[226:227]
	v_mov_b32_e32 v165, 0x276000
	v_add_co_u32_e64 v220, s[18:19], v165, v174
	s_nop 1
	v_addc_co_u32_e64 v221, s[18:19], 0, v175, s[18:19]
	global_load_dwordx4 v[220:223], v[220:221], off
	v_mov_b32_e32 v165, 0x48000
	v_add_co_u32_e64 v224, s[18:19], v165, v176
	s_nop 1
	v_addc_co_u32_e64 v225, s[18:19], 0, v177, s[18:19]
	global_load_dwordx4 v[224:227], v[224:225], off
	v_lshlrev_b32_e32 v110, 16, v100
	v_and_b32_e32 v111, 0xffff0000, v100
	v_lshlrev_b32_e32 v112, 16, v104
	v_and_b32_e32 v113, 0xffff0000, v104
	v_lshlrev_b32_e32 v100, 16, v101
	v_and_b32_e32 v101, 0xffff0000, v101
	v_lshlrev_b32_e32 v104, 16, v105
	v_and_b32_e32 v105, 0xffff0000, v105
	v_pk_fma_f32 v[96:97], v[96:97], v[100:101], v[104:105]
	v_lshlrev_b32_e32 v100, 16, v102
	v_and_b32_e32 v101, 0xffff0000, v102
	v_lshlrev_b32_e32 v104, 16, v106
	v_and_b32_e32 v105, 0xffff0000, v106
	v_pk_fma_f32 v[100:101], v[90:91], v[100:101], v[104:105]
	v_lshlrev_b32_e32 v90, 16, v103
	v_and_b32_e32 v91, 0xffff0000, v103
	v_lshlrev_b32_e32 v102, 16, v107
	v_and_b32_e32 v103, 0xffff0000, v107
	v_pk_fma_f32 v[94:95], v[94:95], v[110:111], v[112:113]
	v_pk_fma_f32 v[102:103], v[92:93], v[90:91], v[102:103]
	v_cvt_pk_bf16_f32 v90, v94, v95
	v_cvt_pk_bf16_f32 v91, v96, v97
	v_cvt_pk_bf16_f32 v92, v100, v101
	v_cvt_pk_bf16_f32 v93, v102, v103
	global_store_dwordx4 v[98:99], v[90:93], off
	s_waitcnt vmcnt(16)
	s_nop 1
	v_mov_b64_e32 v[90:91], v[228:229]
	v_mov_b64_e32 v[92:93], v[230:231]
	s_nop 0
	s_waitcnt vmcnt(15)
	s_nop 1
	v_mov_b64_e32 v[94:95], v[232:233]
	v_mov_b64_e32 v[96:97], v[234:235]
	v_mov_b32_e32 v165, 0x276000
	v_add_co_u32_e64 v228, s[18:19], v165, v174
	s_nop 1
	v_addc_co_u32_e64 v229, s[18:19], 0, v175, s[18:19]
	global_load_dwordx4 v[228:231], v[228:229], off offset:256
	v_mov_b32_e32 v165, 0x48000
	v_add_co_u32_e64 v232, s[18:19], v165, v176
	s_nop 1
	v_addc_co_u32_e64 v233, s[18:19], 0, v177, s[18:19]
	global_load_dwordx4 v[232:235], v[232:233], off offset:256
	v_lshlrev_b32_e32 v100, 16, v90
	v_and_b32_e32 v101, 0xffff0000, v90
	v_lshlrev_b32_e32 v102, 16, v94
	v_and_b32_e32 v103, 0xffff0000, v94
	v_lshlrev_b32_e32 v90, 16, v91
	v_and_b32_e32 v91, 0xffff0000, v91
	v_lshlrev_b32_e32 v94, 16, v95
	v_and_b32_e32 v95, 0xffff0000, v95
	v_pk_fma_f32 v[88:89], v[88:89], v[90:91], v[94:95]
	v_lshlrev_b32_e32 v90, 16, v92
	v_and_b32_e32 v91, 0xffff0000, v92
	v_lshlrev_b32_e32 v94, 16, v96
	v_and_b32_e32 v95, 0xffff0000, v96
	v_pk_fma_f32 v[90:91], v[82:83], v[90:91], v[94:95]
	v_lshlrev_b32_e32 v82, 16, v93
	v_and_b32_e32 v83, 0xffff0000, v93
	v_lshlrev_b32_e32 v92, 16, v97
	v_and_b32_e32 v93, 0xffff0000, v97
	v_pk_fma_f32 v[86:87], v[86:87], v[100:101], v[102:103]
	v_pk_fma_f32 v[92:93], v[84:85], v[82:83], v[92:93]
	v_cvt_pk_bf16_f32 v82, v86, v87
	v_cvt_pk_bf16_f32 v83, v88, v89
	v_cvt_pk_bf16_f32 v84, v90, v91
	v_cvt_pk_bf16_f32 v85, v92, v93
	global_store_dwordx4 v[98:99], v[82:85], off offset:256
	s_nop 1
	v_or_b32_e32 v82, 48, v142
	v_ashrrev_i32_e32 v83, 31, v82
	v_lshlrev_b64 v[88:89], 11, v[82:83]
	v_mad_i64_i32 v[82:83], s[18:19], v82, s63, v[144:145]
	v_lshl_add_u64 v[92:93], v[82:83], 0, v[140:141]
	v_lshl_add_u64 v[82:83], s[4:5], 0, v[88:89]
	v_lshl_add_u64 v[82:83], v[82:83], 0, v[140:141]
	s_waitcnt vmcnt(17)
	s_nop 1
	v_mov_b64_e32 v[84:85], v[236:237]
	v_mov_b64_e32 v[86:87], v[238:239]
	s_waitcnt vmcnt(16)
	s_nop 1
	v_mov_b64_e32 v[88:89], v[240:241]
	v_mov_b64_e32 v[90:91], v[242:243]
	v_mov_b32_e32 v165, 0x2bc000
	v_add_co_u32_e64 v236, s[18:19], v165, v174
	s_nop 1
	v_addc_co_u32_e64 v237, s[18:19], 0, v175, s[18:19]
	global_load_dwordx4 v[236:239], v[236:237], off
	v_mov_b32_e32 v165, 0x50000
	v_add_co_u32_e64 v240, s[18:19], v165, v176
	s_nop 1
	v_addc_co_u32_e64 v241, s[18:19], 0, v177, s[18:19]
	global_load_dwordx4 v[240:243], v[240:241], off
	v_lshlrev_b32_e32 v94, 16, v84
	v_and_b32_e32 v95, 0xffff0000, v84
	v_lshlrev_b32_e32 v96, 16, v88
	v_and_b32_e32 v97, 0xffff0000, v88
	v_lshlrev_b32_e32 v84, 16, v85
	v_and_b32_e32 v85, 0xffff0000, v85
	v_lshlrev_b32_e32 v88, 16, v89
	v_and_b32_e32 v89, 0xffff0000, v89
	v_pk_fma_f32 v[80:81], v[80:81], v[84:85], v[88:89]
	v_lshlrev_b32_e32 v84, 16, v86
	v_and_b32_e32 v85, 0xffff0000, v86
	v_lshlrev_b32_e32 v88, 16, v90
	v_and_b32_e32 v89, 0xffff0000, v90
	v_pk_fma_f32 v[84:85], v[74:75], v[84:85], v[88:89]
	v_lshlrev_b32_e32 v74, 16, v87
	v_and_b32_e32 v75, 0xffff0000, v87
	v_lshlrev_b32_e32 v86, 16, v91
	v_and_b32_e32 v87, 0xffff0000, v91
	v_pk_fma_f32 v[78:79], v[78:79], v[94:95], v[96:97]
	v_pk_fma_f32 v[86:87], v[76:77], v[74:75], v[86:87]
	v_cvt_pk_bf16_f32 v74, v78, v79
	v_cvt_pk_bf16_f32 v75, v80, v81
	v_cvt_pk_bf16_f32 v76, v84, v85
	v_cvt_pk_bf16_f32 v77, v86, v87
	global_store_dwordx4 v[82:83], v[74:77], off
	s_waitcnt vmcnt(17)
	s_nop 1
	v_mov_b64_e32 v[74:75], v[184:185]
	v_mov_b64_e32 v[76:77], v[186:187]
	s_nop 0
	s_waitcnt vmcnt(16)
	s_nop 1
	v_mov_b64_e32 v[78:79], v[188:189]
	v_mov_b64_e32 v[80:81], v[190:191]
	v_mov_b32_e32 v165, 0x2bc000
	v_add_co_u32_e64 v184, s[18:19], v165, v174
	s_nop 1
	v_addc_co_u32_e64 v185, s[18:19], 0, v175, s[18:19]
	global_load_dwordx4 v[184:187], v[184:185], off offset:256
	v_mov_b32_e32 v165, 0x50000
	v_add_co_u32_e64 v188, s[18:19], v165, v176
	s_nop 1
	v_addc_co_u32_e64 v189, s[18:19], 0, v177, s[18:19]
	global_load_dwordx4 v[188:191], v[188:189], off offset:256
	v_lshlrev_b32_e32 v84, 16, v74
	v_and_b32_e32 v85, 0xffff0000, v74
	v_lshlrev_b32_e32 v86, 16, v78
	v_and_b32_e32 v87, 0xffff0000, v78
	v_lshlrev_b32_e32 v74, 16, v75
	v_and_b32_e32 v75, 0xffff0000, v75
	v_lshlrev_b32_e32 v78, 16, v79
	v_and_b32_e32 v79, 0xffff0000, v79
	v_pk_fma_f32 v[72:73], v[72:73], v[74:75], v[78:79]
	v_lshlrev_b32_e32 v74, 16, v76
	v_and_b32_e32 v75, 0xffff0000, v76
	v_lshlrev_b32_e32 v78, 16, v80
	v_and_b32_e32 v79, 0xffff0000, v80
	v_pk_fma_f32 v[74:75], v[66:67], v[74:75], v[78:79]
	v_lshlrev_b32_e32 v66, 16, v77
	v_and_b32_e32 v67, 0xffff0000, v77
	v_lshlrev_b32_e32 v76, 16, v81
	v_and_b32_e32 v77, 0xffff0000, v81
	v_pk_fma_f32 v[70:71], v[70:71], v[84:85], v[86:87]
	v_pk_fma_f32 v[76:77], v[68:69], v[66:67], v[76:77]
	v_cvt_pk_bf16_f32 v66, v70, v71
	v_cvt_pk_bf16_f32 v67, v72, v73
	v_cvt_pk_bf16_f32 v68, v74, v75
	v_cvt_pk_bf16_f32 v69, v76, v77
	global_store_dwordx4 v[82:83], v[66:69], off offset:256
	s_nop 1
	v_add_u32_e32 v66, 0x80, v142
	v_ashrrev_i32_e32 v67, 31, v66
	v_lshlrev_b64 v[72:73], 11, v[66:67]
	v_mad_i64_i32 v[66:67], s[18:19], v66, s63, v[144:145]
	v_lshl_add_u64 v[76:77], v[66:67], 0, v[140:141]
	v_lshl_add_u64 v[66:67], s[4:5], 0, v[72:73]
	v_lshl_add_u64 v[66:67], v[66:67], 0, v[140:141]
	s_waitcnt vmcnt(17)
	s_nop 1
	v_mov_b64_e32 v[68:69], v[204:205]
	v_mov_b64_e32 v[70:71], v[206:207]
	s_waitcnt vmcnt(16)
	s_nop 1
	v_mov_b64_e32 v[72:73], v[208:209]
	v_mov_b64_e32 v[74:75], v[210:211]
	v_mov_b32_e32 v165, 0x302000
	v_add_co_u32_e64 v204, s[18:19], v165, v174
	s_nop 1
	v_addc_co_u32_e64 v205, s[18:19], 0, v175, s[18:19]
	global_load_dwordx4 v[204:207], v[204:205], off
	v_mov_b32_e32 v165, 0x58000
	v_add_co_u32_e64 v208, s[18:19], v165, v176
	s_nop 1
	v_addc_co_u32_e64 v209, s[18:19], 0, v177, s[18:19]
	global_load_dwordx4 v[208:211], v[208:209], off
	v_lshlrev_b32_e32 v78, 16, v68
	v_and_b32_e32 v79, 0xffff0000, v68
	v_lshlrev_b32_e32 v80, 16, v72
	v_and_b32_e32 v81, 0xffff0000, v72
	v_lshlrev_b32_e32 v68, 16, v69
	v_and_b32_e32 v69, 0xffff0000, v69
	v_lshlrev_b32_e32 v72, 16, v73
	v_and_b32_e32 v73, 0xffff0000, v73
	v_pk_fma_f32 v[64:65], v[64:65], v[68:69], v[72:73]
	v_lshlrev_b32_e32 v68, 16, v70
	v_and_b32_e32 v69, 0xffff0000, v70
	v_lshlrev_b32_e32 v72, 16, v74
	v_and_b32_e32 v73, 0xffff0000, v74
	v_pk_fma_f32 v[68:69], v[58:59], v[68:69], v[72:73]
	v_lshlrev_b32_e32 v58, 16, v71
	v_and_b32_e32 v59, 0xffff0000, v71
	v_lshlrev_b32_e32 v70, 16, v75
	v_and_b32_e32 v71, 0xffff0000, v75
	v_pk_fma_f32 v[62:63], v[62:63], v[78:79], v[80:81]
	v_pk_fma_f32 v[70:71], v[60:61], v[58:59], v[70:71]
	v_cvt_pk_bf16_f32 v58, v62, v63
	v_cvt_pk_bf16_f32 v59, v64, v65
	v_cvt_pk_bf16_f32 v60, v68, v69
	v_cvt_pk_bf16_f32 v61, v70, v71
	global_store_dwordx4 v[66:67], v[58:61], off
	s_waitcnt vmcnt(17)
	s_nop 1
	v_mov_b64_e32 v[58:59], v[212:213]
	v_mov_b64_e32 v[60:61], v[214:215]
	s_nop 0
	s_waitcnt vmcnt(16)
	s_nop 1
	v_mov_b64_e32 v[62:63], v[216:217]
	v_mov_b64_e32 v[64:65], v[218:219]
	v_mov_b32_e32 v165, 0x302000
	v_add_co_u32_e64 v212, s[18:19], v165, v174
	s_nop 1
	v_addc_co_u32_e64 v213, s[18:19], 0, v175, s[18:19]
	global_load_dwordx4 v[212:215], v[212:213], off offset:256
	v_mov_b32_e32 v165, 0x58000
	v_add_co_u32_e64 v216, s[18:19], v165, v176
	s_nop 1
	v_addc_co_u32_e64 v217, s[18:19], 0, v177, s[18:19]
	global_load_dwordx4 v[216:219], v[216:217], off offset:256
	v_lshlrev_b32_e32 v68, 16, v58
	v_and_b32_e32 v69, 0xffff0000, v58
	v_lshlrev_b32_e32 v70, 16, v62
	v_and_b32_e32 v71, 0xffff0000, v62
	v_lshlrev_b32_e32 v58, 16, v59
	v_and_b32_e32 v59, 0xffff0000, v59
	v_lshlrev_b32_e32 v62, 16, v63
	v_and_b32_e32 v63, 0xffff0000, v63
	v_pk_fma_f32 v[56:57], v[56:57], v[58:59], v[62:63]
	v_lshlrev_b32_e32 v58, 16, v60
	v_and_b32_e32 v59, 0xffff0000, v60
	v_lshlrev_b32_e32 v62, 16, v64
	v_and_b32_e32 v63, 0xffff0000, v64
	v_pk_fma_f32 v[58:59], v[50:51], v[58:59], v[62:63]
	v_lshlrev_b32_e32 v50, 16, v61
	v_and_b32_e32 v51, 0xffff0000, v61
	v_lshlrev_b32_e32 v60, 16, v65
	v_and_b32_e32 v61, 0xffff0000, v65
	v_pk_fma_f32 v[54:55], v[54:55], v[68:69], v[70:71]
	v_pk_fma_f32 v[60:61], v[52:53], v[50:51], v[60:61]
	v_cvt_pk_bf16_f32 v50, v54, v55
	v_cvt_pk_bf16_f32 v51, v56, v57
	v_cvt_pk_bf16_f32 v52, v58, v59
	v_cvt_pk_bf16_f32 v53, v60, v61
	global_store_dwordx4 v[66:67], v[50:53], off offset:256
	s_nop 1
	v_add_u32_e32 v50, 0x90, v142
	v_ashrrev_i32_e32 v51, 31, v50
	v_lshlrev_b64 v[56:57], 11, v[50:51]
	v_mad_i64_i32 v[50:51], s[18:19], v50, s63, v[144:145]
	v_lshl_add_u64 v[60:61], v[50:51], 0, v[140:141]
	v_lshl_add_u64 v[50:51], s[4:5], 0, v[56:57]
	v_lshl_add_u64 v[50:51], v[50:51], 0, v[140:141]
	s_waitcnt vmcnt(17)
	s_nop 1
	v_mov_b64_e32 v[52:53], v[220:221]
	v_mov_b64_e32 v[54:55], v[222:223]
	s_waitcnt vmcnt(16)
	s_nop 1
	v_mov_b64_e32 v[56:57], v[224:225]
	v_mov_b64_e32 v[58:59], v[226:227]
	v_lshlrev_b32_e32 v62, 16, v52
	v_and_b32_e32 v63, 0xffff0000, v52
	v_lshlrev_b32_e32 v64, 16, v56
	v_and_b32_e32 v65, 0xffff0000, v56
	v_lshlrev_b32_e32 v52, 16, v53
	v_and_b32_e32 v53, 0xffff0000, v53
	v_lshlrev_b32_e32 v56, 16, v57
	v_and_b32_e32 v57, 0xffff0000, v57
	v_pk_fma_f32 v[48:49], v[48:49], v[52:53], v[56:57]
	v_lshlrev_b32_e32 v52, 16, v54
	v_and_b32_e32 v53, 0xffff0000, v54
	v_lshlrev_b32_e32 v56, 16, v58
	v_and_b32_e32 v57, 0xffff0000, v58
	v_pk_fma_f32 v[52:53], v[42:43], v[52:53], v[56:57]
	v_lshlrev_b32_e32 v42, 16, v55
	v_and_b32_e32 v43, 0xffff0000, v55
	v_lshlrev_b32_e32 v54, 16, v59
	v_and_b32_e32 v55, 0xffff0000, v59
	v_pk_fma_f32 v[46:47], v[46:47], v[62:63], v[64:65]
	v_pk_fma_f32 v[54:55], v[44:45], v[42:43], v[54:55]
	v_cvt_pk_bf16_f32 v42, v46, v47
	v_cvt_pk_bf16_f32 v43, v48, v49
	v_cvt_pk_bf16_f32 v44, v52, v53
	v_cvt_pk_bf16_f32 v45, v54, v55
	global_store_dwordx4 v[50:51], v[42:45], off
	s_waitcnt vmcnt(15)
	s_nop 1
	v_mov_b64_e32 v[42:43], v[228:229]
	v_mov_b64_e32 v[44:45], v[230:231]
	s_nop 0
	s_waitcnt vmcnt(14)
	s_nop 1
	v_mov_b64_e32 v[46:47], v[232:233]
	v_mov_b64_e32 v[48:49], v[234:235]
	v_lshlrev_b32_e32 v52, 16, v42
	v_and_b32_e32 v53, 0xffff0000, v42
	v_lshlrev_b32_e32 v54, 16, v46
	v_and_b32_e32 v55, 0xffff0000, v46
	v_lshlrev_b32_e32 v42, 16, v43
	v_and_b32_e32 v43, 0xffff0000, v43
	v_lshlrev_b32_e32 v46, 16, v47
	v_and_b32_e32 v47, 0xffff0000, v47
	v_pk_fma_f32 v[40:41], v[40:41], v[42:43], v[46:47]
	v_lshlrev_b32_e32 v42, 16, v44
	v_and_b32_e32 v43, 0xffff0000, v44
	v_lshlrev_b32_e32 v46, 16, v48
	v_and_b32_e32 v47, 0xffff0000, v48
	v_pk_fma_f32 v[42:43], v[34:35], v[42:43], v[46:47]
	v_lshlrev_b32_e32 v34, 16, v45
	v_and_b32_e32 v35, 0xffff0000, v45
	v_lshlrev_b32_e32 v44, 16, v49
	v_and_b32_e32 v45, 0xffff0000, v49
	v_pk_fma_f32 v[38:39], v[38:39], v[52:53], v[54:55]
	v_pk_fma_f32 v[44:45], v[36:37], v[34:35], v[44:45]
	v_cvt_pk_bf16_f32 v34, v38, v39
	v_cvt_pk_bf16_f32 v35, v40, v41
	v_cvt_pk_bf16_f32 v36, v42, v43
	v_cvt_pk_bf16_f32 v37, v44, v45
	global_store_dwordx4 v[50:51], v[34:37], off offset:256
	s_nop 1
	v_add_u32_e32 v34, 0xa0, v142
	v_ashrrev_i32_e32 v35, 31, v34
	v_lshlrev_b64 v[40:41], 11, v[34:35]
	v_mad_i64_i32 v[34:35], s[18:19], v34, s63, v[144:145]
	v_lshl_add_u64 v[44:45], v[34:35], 0, v[140:141]
	v_lshl_add_u64 v[34:35], s[4:5], 0, v[40:41]
	v_lshl_add_u64 v[34:35], v[34:35], 0, v[140:141]
	s_waitcnt vmcnt(13)
	s_nop 1
	v_mov_b64_e32 v[36:37], v[236:237]
	v_mov_b64_e32 v[38:39], v[238:239]
	s_waitcnt vmcnt(12)
	s_nop 1
	v_mov_b64_e32 v[40:41], v[240:241]
	v_mov_b64_e32 v[42:43], v[242:243]
	v_lshlrev_b32_e32 v46, 16, v36
	v_and_b32_e32 v47, 0xffff0000, v36
	v_lshlrev_b32_e32 v48, 16, v40
	v_and_b32_e32 v49, 0xffff0000, v40
	v_lshlrev_b32_e32 v36, 16, v37
	v_and_b32_e32 v37, 0xffff0000, v37
	v_lshlrev_b32_e32 v40, 16, v41
	v_and_b32_e32 v41, 0xffff0000, v41
	v_pk_fma_f32 v[32:33], v[32:33], v[36:37], v[40:41]
	v_lshlrev_b32_e32 v36, 16, v38
	v_and_b32_e32 v37, 0xffff0000, v38
	v_lshlrev_b32_e32 v40, 16, v42
	v_and_b32_e32 v41, 0xffff0000, v42
	v_pk_fma_f32 v[36:37], v[26:27], v[36:37], v[40:41]
	v_lshlrev_b32_e32 v26, 16, v39
	v_and_b32_e32 v27, 0xffff0000, v39
	v_lshlrev_b32_e32 v38, 16, v43
	v_and_b32_e32 v39, 0xffff0000, v43
	v_pk_fma_f32 v[30:31], v[30:31], v[46:47], v[48:49]
	v_pk_fma_f32 v[38:39], v[28:29], v[26:27], v[38:39]
	v_cvt_pk_bf16_f32 v26, v30, v31
	v_cvt_pk_bf16_f32 v27, v32, v33
	v_cvt_pk_bf16_f32 v28, v36, v37
	v_cvt_pk_bf16_f32 v29, v38, v39
	global_store_dwordx4 v[34:35], v[26:29], off
	s_waitcnt vmcnt(11)
	s_nop 1
	v_mov_b64_e32 v[26:27], v[184:185]
	v_mov_b64_e32 v[28:29], v[186:187]
	s_nop 0
	s_waitcnt vmcnt(10)
	s_nop 1
	v_mov_b64_e32 v[30:31], v[188:189]
	v_mov_b64_e32 v[32:33], v[190:191]
	v_lshlrev_b32_e32 v36, 16, v26
	v_and_b32_e32 v37, 0xffff0000, v26
	v_lshlrev_b32_e32 v38, 16, v30
	v_and_b32_e32 v39, 0xffff0000, v30
	v_lshlrev_b32_e32 v26, 16, v27
	v_and_b32_e32 v27, 0xffff0000, v27
	v_lshlrev_b32_e32 v30, 16, v31
	v_and_b32_e32 v31, 0xffff0000, v31
	v_pk_fma_f32 v[24:25], v[24:25], v[26:27], v[30:31]
	v_lshlrev_b32_e32 v26, 16, v28
	v_and_b32_e32 v27, 0xffff0000, v28
	v_lshlrev_b32_e32 v30, 16, v32
	v_and_b32_e32 v31, 0xffff0000, v32
	v_pk_fma_f32 v[26:27], v[18:19], v[26:27], v[30:31]
	v_lshlrev_b32_e32 v18, 16, v29
	v_and_b32_e32 v19, 0xffff0000, v29
	v_lshlrev_b32_e32 v28, 16, v33
	v_and_b32_e32 v29, 0xffff0000, v33
	v_pk_fma_f32 v[22:23], v[22:23], v[36:37], v[38:39]
	v_pk_fma_f32 v[28:29], v[20:21], v[18:19], v[28:29]
	v_cvt_pk_bf16_f32 v18, v22, v23
	v_cvt_pk_bf16_f32 v19, v24, v25
	v_cvt_pk_bf16_f32 v20, v26, v27
	v_cvt_pk_bf16_f32 v21, v28, v29
	global_store_dwordx4 v[34:35], v[18:21], off offset:256
	s_nop 1
	v_add_u32_e32 v18, 0xb0, v142
	v_ashrrev_i32_e32 v19, 31, v18
	v_lshlrev_b64 v[24:25], 11, v[18:19]
	v_mad_i64_i32 v[18:19], s[18:19], v18, s63, v[144:145]
	v_lshl_add_u64 v[28:29], v[18:19], 0, v[140:141]
	v_lshl_add_u64 v[18:19], s[4:5], 0, v[24:25]
	v_lshl_add_u64 v[18:19], v[18:19], 0, v[140:141]
	s_waitcnt vmcnt(9)
	s_nop 1
	v_mov_b64_e32 v[20:21], v[204:205]
	v_mov_b64_e32 v[22:23], v[206:207]
	s_waitcnt vmcnt(8)
	s_nop 1
	v_mov_b64_e32 v[24:25], v[208:209]
	v_mov_b64_e32 v[26:27], v[210:211]
	s_mov_b64 s[18:19], -1
	v_lshlrev_b32_e32 v30, 16, v20
	v_and_b32_e32 v31, 0xffff0000, v20
	v_lshlrev_b32_e32 v32, 16, v24
	v_and_b32_e32 v33, 0xffff0000, v24
	v_lshlrev_b32_e32 v20, 16, v21
	v_and_b32_e32 v21, 0xffff0000, v21
	v_lshlrev_b32_e32 v24, 16, v25
	v_and_b32_e32 v25, 0xffff0000, v25
	v_pk_fma_f32 v[16:17], v[16:17], v[20:21], v[24:25]
	v_lshlrev_b32_e32 v20, 16, v22
	v_and_b32_e32 v21, 0xffff0000, v22
	v_lshlrev_b32_e32 v24, 16, v26
	v_and_b32_e32 v25, 0xffff0000, v26
	v_pk_fma_f32 v[20:21], v[10:11], v[20:21], v[24:25]
	v_lshlrev_b32_e32 v10, 16, v23
	v_and_b32_e32 v11, 0xffff0000, v23
	v_lshlrev_b32_e32 v22, 16, v27
	v_and_b32_e32 v23, 0xffff0000, v27
	v_pk_fma_f32 v[14:15], v[14:15], v[30:31], v[32:33]
	v_pk_fma_f32 v[22:23], v[12:13], v[10:11], v[22:23]
	v_cvt_pk_bf16_f32 v10, v14, v15
	v_cvt_pk_bf16_f32 v11, v16, v17
	v_cvt_pk_bf16_f32 v12, v20, v21
	v_cvt_pk_bf16_f32 v13, v22, v23
	global_store_dwordx4 v[18:19], v[10:13], off
	s_waitcnt vmcnt(7)
	s_nop 1
	v_mov_b64_e32 v[10:11], v[212:213]
	v_mov_b64_e32 v[12:13], v[214:215]
	s_nop 0
	s_waitcnt vmcnt(6)
	s_nop 1
	v_mov_b64_e32 v[14:15], v[216:217]
	v_mov_b64_e32 v[16:17], v[218:219]
	v_lshlrev_b32_e32 v20, 16, v10
	v_and_b32_e32 v21, 0xffff0000, v10
	v_lshlrev_b32_e32 v22, 16, v14
	v_and_b32_e32 v23, 0xffff0000, v14
	v_lshlrev_b32_e32 v10, 16, v11
	v_and_b32_e32 v11, 0xffff0000, v11
	v_lshlrev_b32_e32 v14, 16, v15
	v_and_b32_e32 v15, 0xffff0000, v15
	v_pk_fma_f32 v[8:9], v[8:9], v[10:11], v[14:15]
	v_lshlrev_b32_e32 v10, 16, v12
	v_and_b32_e32 v11, 0xffff0000, v12
	v_lshlrev_b32_e32 v14, 16, v16
	v_and_b32_e32 v15, 0xffff0000, v16
	v_pk_fma_f32 v[10:11], v[2:3], v[10:11], v[14:15]
	v_lshlrev_b32_e32 v2, 16, v13
	v_and_b32_e32 v3, 0xffff0000, v13
	v_lshlrev_b32_e32 v12, 16, v17
	v_and_b32_e32 v13, 0xffff0000, v17
	v_pk_fma_f32 v[6:7], v[6:7], v[20:21], v[22:23]
	v_pk_fma_f32 v[12:13], v[4:5], v[2:3], v[12:13]
	v_cvt_pk_bf16_f32 v2, v6, v7
	v_cvt_pk_bf16_f32 v3, v8, v9
	v_cvt_pk_bf16_f32 v4, v10, v11
	v_cvt_pk_bf16_f32 v5, v12, v13
	global_store_dwordx4 v[18:19], v[2:5], off offset:256
	s_cbranch_vccnz .LBB0_1414
	s_andn2_b64 vcc, exec, s[6:7]
	s_cbranch_vccnz .LBB0_1413
	s_barrier
	s_branch .LBB0_1413

.LBB0_1449:
	v_lshl_add_u32 v138, s55, 8, v142
	v_lshl_or_b32 v136, s54, 8, v144
	v_ashrrev_i32_e32 v139, 31, v138
	v_ashrrev_i32_e32 v137, 31, v136
	v_lshlrev_b64 v[166:167], 11, v[138:139]
	v_mov_b64_e32 v[140:141], s[10:11]
	v_mad_i64_i32 v[162:163], s[22:23], v138, s63, v[140:141]
	v_lshlrev_b64 v[136:137], 1, v[136:137]
	v_lshl_add_u64 v[166:167], s[4:5], 0, v[166:167]
	v_lshl_add_u64 v[170:171], v[162:163], 0, v[136:137]
	v_lshl_add_u64 v[172:173], v[166:167], 0, v[136:137]
	global_load_dwordx4 v[162:165], v[170:171], off
	global_load_dwordx4 v[166:169], v[172:173], off
	global_load_dwordx4 v[182:185], v[170:171], off offset:256
	global_load_dwordx4 v[186:189], v[172:173], off offset:256
	v_mov_b32_e32 v160, 0x46000
	v_add_co_u32_e64 v204, s[22:23], v160, v170
	s_nop 1
	v_addc_co_u32_e64 v205, s[22:23], 0, v171, s[22:23]
	global_load_dwordx4 v[204:207], v[204:205], off
	v_mov_b32_e32 v160, 0x8000
	v_add_co_u32_e64 v208, s[22:23], v160, v172
	s_nop 1
	v_addc_co_u32_e64 v209, s[22:23], 0, v173, s[22:23]
	global_load_dwordx4 v[208:211], v[208:209], off
	v_mov_b32_e32 v160, 0x46000
	v_add_co_u32_e64 v212, s[22:23], v160, v170
	s_nop 1
	v_addc_co_u32_e64 v213, s[22:23], 0, v171, s[22:23]
	global_load_dwordx4 v[212:215], v[212:213], off offset:256
	v_mov_b32_e32 v160, 0x8000
	v_add_co_u32_e64 v216, s[22:23], v160, v172
	s_nop 1
	v_addc_co_u32_e64 v217, s[22:23], 0, v173, s[22:23]
	global_load_dwordx4 v[216:219], v[216:217], off offset:256
	v_mov_b32_e32 v160, 0x8c000
	v_add_co_u32_e64 v220, s[22:23], v160, v170
	s_nop 1
	v_addc_co_u32_e64 v221, s[22:23], 0, v171, s[22:23]
	global_load_dwordx4 v[220:223], v[220:221], off
	v_mov_b32_e32 v160, 0x10000
	v_add_co_u32_e64 v224, s[22:23], v160, v172
	s_nop 1
	v_addc_co_u32_e64 v225, s[22:23], 0, v173, s[22:23]
	global_load_dwordx4 v[224:227], v[224:225], off
	v_mov_b32_e32 v160, 0x8c000
	v_add_co_u32_e64 v228, s[22:23], v160, v170
	s_nop 1
	v_addc_co_u32_e64 v229, s[22:23], 0, v171, s[22:23]
	global_load_dwordx4 v[228:231], v[228:229], off offset:256
	v_mov_b32_e32 v160, 0x10000
	v_add_co_u32_e64 v232, s[22:23], v160, v172
	s_nop 1
	v_addc_co_u32_e64 v233, s[22:23], 0, v173, s[22:23]
	global_load_dwordx4 v[232:235], v[232:233], off offset:256
	v_mov_b32_e32 v160, 0xd2000
	v_add_co_u32_e64 v236, s[22:23], v160, v170
	s_nop 1
	v_addc_co_u32_e64 v237, s[22:23], 0, v171, s[22:23]
	global_load_dwordx4 v[236:239], v[236:237], off
	v_mov_b32_e32 v160, 0x18000
	v_add_co_u32_e64 v240, s[22:23], v160, v172
	s_nop 1
	v_addc_co_u32_e64 v241, s[22:23], 0, v173, s[22:23]
	global_load_dwordx4 v[240:243], v[240:241], off
	s_andn2_b64 vcc, exec, s[8:9]
	v_readlane_b32 s56, v250, 59
	v_readlane_b32 s57, v250, 60
	v_readlane_b32 s58, v250, 61
	s_waitcnt vmcnt(12)
	v_lshlrev_b32_e32 v174, 16, v162
	v_and_b32_e32 v175, 0xffff0000, v162
	v_lshlrev_b32_e32 v176, 16, v166
	v_and_b32_e32 v177, 0xffff0000, v166
	v_lshlrev_b32_e32 v162, 16, v163
	v_and_b32_e32 v163, 0xffff0000, v163
	v_lshlrev_b32_e32 v166, 16, v167
	v_and_b32_e32 v167, 0xffff0000, v167
	v_pk_fma_f32 v[128:129], v[128:129], v[162:163], v[166:167]
	v_lshlrev_b32_e32 v162, 16, v164
	v_and_b32_e32 v163, 0xffff0000, v164
	v_lshlrev_b32_e32 v166, 16, v168
	v_and_b32_e32 v167, 0xffff0000, v168
	v_pk_fma_f32 v[162:163], v[122:123], v[162:163], v[166:167]
	v_lshlrev_b32_e32 v122, 16, v165
	v_and_b32_e32 v123, 0xffff0000, v165
	v_lshlrev_b32_e32 v164, 16, v169
	v_and_b32_e32 v165, 0xffff0000, v169
	v_pk_fma_f32 v[126:127], v[126:127], v[174:175], v[176:177]
	v_pk_fma_f32 v[164:165], v[124:125], v[122:123], v[164:165]
	v_cvt_pk_bf16_f32 v122, v126, v127
	v_cvt_pk_bf16_f32 v123, v128, v129
	v_cvt_pk_bf16_f32 v124, v162, v163
	v_cvt_pk_bf16_f32 v125, v164, v165
	global_store_dwordx4 v[172:173], v[122:125], off
	s_waitcnt vmcnt(12)
	s_nop 1
	v_mov_b64_e32 v[122:123], v[182:183]
	v_mov_b64_e32 v[124:125], v[184:185]
	s_nop 0
	s_waitcnt vmcnt(11)
	s_nop 1
	v_mov_b64_e32 v[126:127], v[186:187]
	v_mov_b64_e32 v[128:129], v[188:189]
	v_mov_b32_e32 v160, 0xd2000
	v_add_co_u32_e64 v182, s[22:23], v160, v170
	s_nop 1
	v_addc_co_u32_e64 v183, s[22:23], 0, v171, s[22:23]
	global_load_dwordx4 v[182:185], v[182:183], off offset:256
	v_mov_b32_e32 v160, 0x18000
	v_add_co_u32_e64 v186, s[22:23], v160, v172
	s_nop 1
	v_addc_co_u32_e64 v187, s[22:23], 0, v173, s[22:23]
	global_load_dwordx4 v[186:189], v[186:187], off offset:256
	v_lshlrev_b32_e32 v162, 16, v122
	v_and_b32_e32 v163, 0xffff0000, v122
	v_lshlrev_b32_e32 v164, 16, v126
	v_and_b32_e32 v165, 0xffff0000, v126
	v_lshlrev_b32_e32 v122, 16, v123
	v_and_b32_e32 v123, 0xffff0000, v123
	v_lshlrev_b32_e32 v126, 16, v127
	v_and_b32_e32 v127, 0xffff0000, v127
	v_pk_fma_f32 v[120:121], v[120:121], v[122:123], v[126:127]
	v_lshlrev_b32_e32 v122, 16, v124
	v_and_b32_e32 v123, 0xffff0000, v124
	v_lshlrev_b32_e32 v126, 16, v128
	v_and_b32_e32 v127, 0xffff0000, v128
	v_pk_fma_f32 v[122:123], v[114:115], v[122:123], v[126:127]
	v_lshlrev_b32_e32 v114, 16, v125
	v_and_b32_e32 v115, 0xffff0000, v125
	v_lshlrev_b32_e32 v124, 16, v129
	v_and_b32_e32 v125, 0xffff0000, v129
	v_pk_fma_f32 v[118:119], v[118:119], v[162:163], v[164:165]
	v_pk_fma_f32 v[124:125], v[116:117], v[114:115], v[124:125]
	v_cvt_pk_bf16_f32 v114, v118, v119
	v_cvt_pk_bf16_f32 v115, v120, v121
	v_cvt_pk_bf16_f32 v116, v122, v123
	v_cvt_pk_bf16_f32 v117, v124, v125
	global_store_dwordx4 v[172:173], v[114:117], off offset:256
	s_nop 1
	v_or_b32_e32 v114, 16, v138
	v_ashrrev_i32_e32 v115, 31, v114
	v_lshlrev_b64 v[120:121], 11, v[114:115]
	v_mad_i64_i32 v[114:115], s[22:23], v114, s63, v[140:141]
	v_lshl_add_u64 v[124:125], v[114:115], 0, v[136:137]
	v_lshl_add_u64 v[114:115], s[4:5], 0, v[120:121]
	v_lshl_add_u64 v[114:115], v[114:115], 0, v[136:137]
	s_waitcnt vmcnt(13)
	s_nop 1
	v_mov_b64_e32 v[116:117], v[204:205]
	v_mov_b64_e32 v[118:119], v[206:207]
	s_waitcnt vmcnt(12)
	s_nop 1
	v_mov_b64_e32 v[120:121], v[208:209]
	v_mov_b64_e32 v[122:123], v[210:211]
	v_mov_b32_e32 v160, 0x230000
	v_add_co_u32_e64 v204, s[22:23], v160, v170
	s_nop 1
	v_addc_co_u32_e64 v205, s[22:23], 0, v171, s[22:23]
	global_load_dwordx4 v[204:207], v[204:205], off
	v_mov_b32_e32 v160, 0x40000
	v_add_co_u32_e64 v208, s[22:23], v160, v172
	s_nop 1
	v_addc_co_u32_e64 v209, s[22:23], 0, v173, s[22:23]
	global_load_dwordx4 v[208:211], v[208:209], off
	v_lshlrev_b32_e32 v126, 16, v116
	v_and_b32_e32 v127, 0xffff0000, v116
	v_lshlrev_b32_e32 v128, 16, v120
	v_and_b32_e32 v129, 0xffff0000, v120
	v_lshlrev_b32_e32 v116, 16, v117
	v_and_b32_e32 v117, 0xffff0000, v117
	v_lshlrev_b32_e32 v120, 16, v121
	v_and_b32_e32 v121, 0xffff0000, v121
	v_pk_fma_f32 v[112:113], v[112:113], v[116:117], v[120:121]
	v_lshlrev_b32_e32 v116, 16, v118
	v_and_b32_e32 v117, 0xffff0000, v118
	v_lshlrev_b32_e32 v120, 16, v122
	v_and_b32_e32 v121, 0xffff0000, v122
	v_pk_fma_f32 v[116:117], v[106:107], v[116:117], v[120:121]
	v_lshlrev_b32_e32 v106, 16, v119
	v_and_b32_e32 v107, 0xffff0000, v119
	v_lshlrev_b32_e32 v118, 16, v123
	v_and_b32_e32 v119, 0xffff0000, v123
	v_pk_fma_f32 v[110:111], v[110:111], v[126:127], v[128:129]
	v_pk_fma_f32 v[118:119], v[108:109], v[106:107], v[118:119]
	v_cvt_pk_bf16_f32 v106, v110, v111
	v_cvt_pk_bf16_f32 v107, v112, v113
	v_cvt_pk_bf16_f32 v108, v116, v117
	v_cvt_pk_bf16_f32 v109, v118, v119
	global_store_dwordx4 v[114:115], v[106:109], off
	s_waitcnt vmcnt(14)
	s_nop 1
	v_mov_b64_e32 v[106:107], v[212:213]
	v_mov_b64_e32 v[108:109], v[214:215]
	s_nop 0
	s_waitcnt vmcnt(13)
	s_nop 1
	v_mov_b64_e32 v[110:111], v[216:217]
	v_mov_b64_e32 v[112:113], v[218:219]
	v_mov_b32_e32 v160, 0x230000
	v_add_co_u32_e64 v212, s[22:23], v160, v170
	s_nop 1
	v_addc_co_u32_e64 v213, s[22:23], 0, v171, s[22:23]
	global_load_dwordx4 v[212:215], v[212:213], off offset:256
	v_mov_b32_e32 v160, 0x40000
	v_add_co_u32_e64 v216, s[22:23], v160, v172
	s_nop 1
	v_addc_co_u32_e64 v217, s[22:23], 0, v173, s[22:23]
	global_load_dwordx4 v[216:219], v[216:217], off offset:256
	v_lshlrev_b32_e32 v116, 16, v106
	v_and_b32_e32 v117, 0xffff0000, v106
	v_lshlrev_b32_e32 v118, 16, v110
	v_and_b32_e32 v119, 0xffff0000, v110
	v_lshlrev_b32_e32 v106, 16, v107
	v_and_b32_e32 v107, 0xffff0000, v107
	v_lshlrev_b32_e32 v110, 16, v111
	v_and_b32_e32 v111, 0xffff0000, v111
	v_pk_fma_f32 v[104:105], v[104:105], v[106:107], v[110:111]
	v_lshlrev_b32_e32 v106, 16, v108
	v_and_b32_e32 v107, 0xffff0000, v108
	v_lshlrev_b32_e32 v110, 16, v112
	v_and_b32_e32 v111, 0xffff0000, v112
	v_pk_fma_f32 v[106:107], v[98:99], v[106:107], v[110:111]
	v_lshlrev_b32_e32 v98, 16, v109
	v_and_b32_e32 v99, 0xffff0000, v109
	v_lshlrev_b32_e32 v108, 16, v113
	v_and_b32_e32 v109, 0xffff0000, v113
	v_pk_fma_f32 v[102:103], v[102:103], v[116:117], v[118:119]
	v_pk_fma_f32 v[108:109], v[100:101], v[98:99], v[108:109]
	v_cvt_pk_bf16_f32 v98, v102, v103
	v_cvt_pk_bf16_f32 v99, v104, v105
	v_cvt_pk_bf16_f32 v100, v106, v107
	v_cvt_pk_bf16_f32 v101, v108, v109
	global_store_dwordx4 v[114:115], v[98:101], off offset:256
	s_nop 1
	v_or_b32_e32 v98, 32, v138
	v_ashrrev_i32_e32 v99, 31, v98
	v_lshlrev_b64 v[104:105], 11, v[98:99]
	v_mad_i64_i32 v[98:99], s[22:23], v98, s63, v[140:141]
	v_lshl_add_u64 v[108:109], v[98:99], 0, v[136:137]
	v_lshl_add_u64 v[98:99], s[4:5], 0, v[104:105]
	v_lshl_add_u64 v[98:99], v[98:99], 0, v[136:137]
	s_waitcnt vmcnt(15)
	s_nop 1
	v_mov_b64_e32 v[100:101], v[220:221]
	v_mov_b64_e32 v[102:103], v[222:223]
	s_waitcnt vmcnt(14)
	s_nop 1
	v_mov_b64_e32 v[104:105], v[224:225]
	v_mov_b64_e32 v[106:107], v[226:227]
	v_mov_b32_e32 v160, 0x276000
	v_add_co_u32_e64 v220, s[22:23], v160, v170
	s_nop 1
	v_addc_co_u32_e64 v221, s[22:23], 0, v171, s[22:23]
	global_load_dwordx4 v[220:223], v[220:221], off
	v_mov_b32_e32 v160, 0x48000
	v_add_co_u32_e64 v224, s[22:23], v160, v172
	s_nop 1
	v_addc_co_u32_e64 v225, s[22:23], 0, v173, s[22:23]
	global_load_dwordx4 v[224:227], v[224:225], off
	v_lshlrev_b32_e32 v110, 16, v100
	v_and_b32_e32 v111, 0xffff0000, v100
	v_lshlrev_b32_e32 v112, 16, v104
	v_and_b32_e32 v113, 0xffff0000, v104
	v_lshlrev_b32_e32 v100, 16, v101
	v_and_b32_e32 v101, 0xffff0000, v101
	v_lshlrev_b32_e32 v104, 16, v105
	v_and_b32_e32 v105, 0xffff0000, v105
	v_pk_fma_f32 v[96:97], v[96:97], v[100:101], v[104:105]
	v_lshlrev_b32_e32 v100, 16, v102
	v_and_b32_e32 v101, 0xffff0000, v102
	v_lshlrev_b32_e32 v104, 16, v106
	v_and_b32_e32 v105, 0xffff0000, v106
	v_pk_fma_f32 v[100:101], v[90:91], v[100:101], v[104:105]
	v_lshlrev_b32_e32 v90, 16, v103
	v_and_b32_e32 v91, 0xffff0000, v103
	v_lshlrev_b32_e32 v102, 16, v107
	v_and_b32_e32 v103, 0xffff0000, v107
	v_pk_fma_f32 v[94:95], v[94:95], v[110:111], v[112:113]
	v_pk_fma_f32 v[102:103], v[92:93], v[90:91], v[102:103]
	v_cvt_pk_bf16_f32 v90, v94, v95
	v_cvt_pk_bf16_f32 v91, v96, v97
	v_cvt_pk_bf16_f32 v92, v100, v101
	v_cvt_pk_bf16_f32 v93, v102, v103
	global_store_dwordx4 v[98:99], v[90:93], off
	s_waitcnt vmcnt(16)
	s_nop 1
	v_mov_b64_e32 v[90:91], v[228:229]
	v_mov_b64_e32 v[92:93], v[230:231]
	s_nop 0
	s_waitcnt vmcnt(15)
	s_nop 1
	v_mov_b64_e32 v[94:95], v[232:233]
	v_mov_b64_e32 v[96:97], v[234:235]
	v_mov_b32_e32 v160, 0x276000
	v_add_co_u32_e64 v228, s[22:23], v160, v170
	s_nop 1
	v_addc_co_u32_e64 v229, s[22:23], 0, v171, s[22:23]
	global_load_dwordx4 v[228:231], v[228:229], off offset:256
	v_mov_b32_e32 v160, 0x48000
	v_add_co_u32_e64 v232, s[22:23], v160, v172
	s_nop 1
	v_addc_co_u32_e64 v233, s[22:23], 0, v173, s[22:23]
	global_load_dwordx4 v[232:235], v[232:233], off offset:256
	v_lshlrev_b32_e32 v100, 16, v90
	v_and_b32_e32 v101, 0xffff0000, v90
	v_lshlrev_b32_e32 v102, 16, v94
	v_and_b32_e32 v103, 0xffff0000, v94
	v_lshlrev_b32_e32 v90, 16, v91
	v_and_b32_e32 v91, 0xffff0000, v91
	v_lshlrev_b32_e32 v94, 16, v95
	v_and_b32_e32 v95, 0xffff0000, v95
	v_pk_fma_f32 v[88:89], v[88:89], v[90:91], v[94:95]
	v_lshlrev_b32_e32 v90, 16, v92
	v_and_b32_e32 v91, 0xffff0000, v92
	v_lshlrev_b32_e32 v94, 16, v96
	v_and_b32_e32 v95, 0xffff0000, v96
	v_pk_fma_f32 v[90:91], v[82:83], v[90:91], v[94:95]
	v_lshlrev_b32_e32 v82, 16, v93
	v_and_b32_e32 v83, 0xffff0000, v93
	v_lshlrev_b32_e32 v92, 16, v97
	v_and_b32_e32 v93, 0xffff0000, v97
	v_pk_fma_f32 v[86:87], v[86:87], v[100:101], v[102:103]
	v_pk_fma_f32 v[92:93], v[84:85], v[82:83], v[92:93]
	v_cvt_pk_bf16_f32 v82, v86, v87
	v_cvt_pk_bf16_f32 v83, v88, v89
	v_cvt_pk_bf16_f32 v84, v90, v91
	v_cvt_pk_bf16_f32 v85, v92, v93
	global_store_dwordx4 v[98:99], v[82:85], off offset:256
	s_nop 1
	v_or_b32_e32 v82, 48, v138
	v_ashrrev_i32_e32 v83, 31, v82
	v_lshlrev_b64 v[88:89], 11, v[82:83]
	v_mad_i64_i32 v[82:83], s[22:23], v82, s63, v[140:141]
	v_lshl_add_u64 v[92:93], v[82:83], 0, v[136:137]
	v_lshl_add_u64 v[82:83], s[4:5], 0, v[88:89]
	v_lshl_add_u64 v[82:83], v[82:83], 0, v[136:137]
	s_waitcnt vmcnt(17)
	s_nop 1
	v_mov_b64_e32 v[84:85], v[236:237]
	v_mov_b64_e32 v[86:87], v[238:239]
	s_waitcnt vmcnt(16)
	s_nop 1
	v_mov_b64_e32 v[88:89], v[240:241]
	v_mov_b64_e32 v[90:91], v[242:243]
	v_mov_b32_e32 v160, 0x2bc000
	v_add_co_u32_e64 v236, s[22:23], v160, v170
	s_nop 1
	v_addc_co_u32_e64 v237, s[22:23], 0, v171, s[22:23]
	global_load_dwordx4 v[236:239], v[236:237], off
	v_mov_b32_e32 v160, 0x50000
	v_add_co_u32_e64 v240, s[22:23], v160, v172
	s_nop 1
	v_addc_co_u32_e64 v241, s[22:23], 0, v173, s[22:23]
	global_load_dwordx4 v[240:243], v[240:241], off
	v_lshlrev_b32_e32 v94, 16, v84
	v_and_b32_e32 v95, 0xffff0000, v84
	v_lshlrev_b32_e32 v96, 16, v88
	v_and_b32_e32 v97, 0xffff0000, v88
	v_lshlrev_b32_e32 v84, 16, v85
	v_and_b32_e32 v85, 0xffff0000, v85
	v_lshlrev_b32_e32 v88, 16, v89
	v_and_b32_e32 v89, 0xffff0000, v89
	v_pk_fma_f32 v[80:81], v[80:81], v[84:85], v[88:89]
	v_lshlrev_b32_e32 v84, 16, v86
	v_and_b32_e32 v85, 0xffff0000, v86
	v_lshlrev_b32_e32 v88, 16, v90
	v_and_b32_e32 v89, 0xffff0000, v90
	v_pk_fma_f32 v[84:85], v[74:75], v[84:85], v[88:89]
	v_lshlrev_b32_e32 v74, 16, v87
	v_and_b32_e32 v75, 0xffff0000, v87
	v_lshlrev_b32_e32 v86, 16, v91
	v_and_b32_e32 v87, 0xffff0000, v91
	v_pk_fma_f32 v[78:79], v[78:79], v[94:95], v[96:97]
	v_pk_fma_f32 v[86:87], v[76:77], v[74:75], v[86:87]
	v_cvt_pk_bf16_f32 v74, v78, v79
	v_cvt_pk_bf16_f32 v75, v80, v81
	v_cvt_pk_bf16_f32 v76, v84, v85
	v_cvt_pk_bf16_f32 v77, v86, v87
	global_store_dwordx4 v[82:83], v[74:77], off
	s_waitcnt vmcnt(17)
	s_nop 1
	v_mov_b64_e32 v[74:75], v[182:183]
	v_mov_b64_e32 v[76:77], v[184:185]
	s_nop 0
	s_waitcnt vmcnt(16)
	s_nop 1
	v_mov_b64_e32 v[78:79], v[186:187]
	v_mov_b64_e32 v[80:81], v[188:189]
	v_mov_b32_e32 v160, 0x2bc000
	v_add_co_u32_e64 v182, s[22:23], v160, v170
	s_nop 1
	v_addc_co_u32_e64 v183, s[22:23], 0, v171, s[22:23]
	global_load_dwordx4 v[182:185], v[182:183], off offset:256
	v_mov_b32_e32 v160, 0x50000
	v_add_co_u32_e64 v186, s[22:23], v160, v172
	s_nop 1
	v_addc_co_u32_e64 v187, s[22:23], 0, v173, s[22:23]
	global_load_dwordx4 v[186:189], v[186:187], off offset:256
	v_lshlrev_b32_e32 v84, 16, v74
	v_and_b32_e32 v85, 0xffff0000, v74
	v_lshlrev_b32_e32 v86, 16, v78
	v_and_b32_e32 v87, 0xffff0000, v78
	v_lshlrev_b32_e32 v74, 16, v75
	v_and_b32_e32 v75, 0xffff0000, v75
	v_lshlrev_b32_e32 v78, 16, v79
	v_and_b32_e32 v79, 0xffff0000, v79
	v_pk_fma_f32 v[72:73], v[72:73], v[74:75], v[78:79]
	v_lshlrev_b32_e32 v74, 16, v76
	v_and_b32_e32 v75, 0xffff0000, v76
	v_lshlrev_b32_e32 v78, 16, v80
	v_and_b32_e32 v79, 0xffff0000, v80
	v_pk_fma_f32 v[74:75], v[66:67], v[74:75], v[78:79]
	v_lshlrev_b32_e32 v66, 16, v77
	v_and_b32_e32 v67, 0xffff0000, v77
	v_lshlrev_b32_e32 v76, 16, v81
	v_and_b32_e32 v77, 0xffff0000, v81
	v_pk_fma_f32 v[70:71], v[70:71], v[84:85], v[86:87]
	v_pk_fma_f32 v[76:77], v[68:69], v[66:67], v[76:77]
	v_cvt_pk_bf16_f32 v66, v70, v71
	v_cvt_pk_bf16_f32 v67, v72, v73
	v_cvt_pk_bf16_f32 v68, v74, v75
	v_cvt_pk_bf16_f32 v69, v76, v77
	global_store_dwordx4 v[82:83], v[66:69], off offset:256
	s_nop 1
	v_add_u32_e32 v66, 0x80, v138
	v_ashrrev_i32_e32 v67, 31, v66
	v_lshlrev_b64 v[72:73], 11, v[66:67]
	v_mad_i64_i32 v[66:67], s[22:23], v66, s63, v[140:141]
	v_lshl_add_u64 v[76:77], v[66:67], 0, v[136:137]
	v_lshl_add_u64 v[66:67], s[4:5], 0, v[72:73]
	v_lshl_add_u64 v[66:67], v[66:67], 0, v[136:137]
	s_waitcnt vmcnt(17)
	s_nop 1
	v_mov_b64_e32 v[68:69], v[204:205]
	v_mov_b64_e32 v[70:71], v[206:207]
	s_waitcnt vmcnt(16)
	s_nop 1
	v_mov_b64_e32 v[72:73], v[208:209]
	v_mov_b64_e32 v[74:75], v[210:211]
	v_mov_b32_e32 v160, 0x302000
	v_add_co_u32_e64 v204, s[22:23], v160, v170
	s_nop 1
	v_addc_co_u32_e64 v205, s[22:23], 0, v171, s[22:23]
	global_load_dwordx4 v[204:207], v[204:205], off
	v_mov_b32_e32 v160, 0x58000
	v_add_co_u32_e64 v208, s[22:23], v160, v172
	s_nop 1
	v_addc_co_u32_e64 v209, s[22:23], 0, v173, s[22:23]
	global_load_dwordx4 v[208:211], v[208:209], off
	v_lshlrev_b32_e32 v78, 16, v68
	v_and_b32_e32 v79, 0xffff0000, v68
	v_lshlrev_b32_e32 v80, 16, v72
	v_and_b32_e32 v81, 0xffff0000, v72
	v_lshlrev_b32_e32 v68, 16, v69
	v_and_b32_e32 v69, 0xffff0000, v69
	v_lshlrev_b32_e32 v72, 16, v73
	v_and_b32_e32 v73, 0xffff0000, v73
	v_pk_fma_f32 v[64:65], v[64:65], v[68:69], v[72:73]
	v_lshlrev_b32_e32 v68, 16, v70
	v_and_b32_e32 v69, 0xffff0000, v70
	v_lshlrev_b32_e32 v72, 16, v74
	v_and_b32_e32 v73, 0xffff0000, v74
	v_pk_fma_f32 v[68:69], v[58:59], v[68:69], v[72:73]
	v_lshlrev_b32_e32 v58, 16, v71
	v_and_b32_e32 v59, 0xffff0000, v71
	v_lshlrev_b32_e32 v70, 16, v75
	v_and_b32_e32 v71, 0xffff0000, v75
	v_pk_fma_f32 v[62:63], v[62:63], v[78:79], v[80:81]
	v_pk_fma_f32 v[70:71], v[60:61], v[58:59], v[70:71]
	v_cvt_pk_bf16_f32 v58, v62, v63
	v_cvt_pk_bf16_f32 v59, v64, v65
	v_cvt_pk_bf16_f32 v60, v68, v69
	v_cvt_pk_bf16_f32 v61, v70, v71
	global_store_dwordx4 v[66:67], v[58:61], off
	s_waitcnt vmcnt(17)
	s_nop 1
	v_mov_b64_e32 v[58:59], v[212:213]
	v_mov_b64_e32 v[60:61], v[214:215]
	s_nop 0
	s_waitcnt vmcnt(16)
	s_nop 1
	v_mov_b64_e32 v[62:63], v[216:217]
	v_mov_b64_e32 v[64:65], v[218:219]
	v_mov_b32_e32 v160, 0x302000
	v_add_co_u32_e64 v212, s[22:23], v160, v170
	s_nop 1
	v_addc_co_u32_e64 v213, s[22:23], 0, v171, s[22:23]
	global_load_dwordx4 v[212:215], v[212:213], off offset:256
	v_mov_b32_e32 v160, 0x58000
	v_add_co_u32_e64 v216, s[22:23], v160, v172
	s_nop 1
	v_addc_co_u32_e64 v217, s[22:23], 0, v173, s[22:23]
	global_load_dwordx4 v[216:219], v[216:217], off offset:256
	v_lshlrev_b32_e32 v68, 16, v58
	v_and_b32_e32 v69, 0xffff0000, v58
	v_lshlrev_b32_e32 v70, 16, v62
	v_and_b32_e32 v71, 0xffff0000, v62
	v_lshlrev_b32_e32 v58, 16, v59
	v_and_b32_e32 v59, 0xffff0000, v59
	v_lshlrev_b32_e32 v62, 16, v63
	v_and_b32_e32 v63, 0xffff0000, v63
	v_pk_fma_f32 v[56:57], v[56:57], v[58:59], v[62:63]
	v_lshlrev_b32_e32 v58, 16, v60
	v_and_b32_e32 v59, 0xffff0000, v60
	v_lshlrev_b32_e32 v62, 16, v64
	v_and_b32_e32 v63, 0xffff0000, v64
	v_pk_fma_f32 v[58:59], v[50:51], v[58:59], v[62:63]
	v_lshlrev_b32_e32 v50, 16, v61
	v_and_b32_e32 v51, 0xffff0000, v61
	v_lshlrev_b32_e32 v60, 16, v65
	v_and_b32_e32 v61, 0xffff0000, v65
	v_pk_fma_f32 v[54:55], v[54:55], v[68:69], v[70:71]
	v_pk_fma_f32 v[60:61], v[52:53], v[50:51], v[60:61]
	v_cvt_pk_bf16_f32 v50, v54, v55
	v_cvt_pk_bf16_f32 v51, v56, v57
	v_cvt_pk_bf16_f32 v52, v58, v59
	v_cvt_pk_bf16_f32 v53, v60, v61
	global_store_dwordx4 v[66:67], v[50:53], off offset:256
	s_nop 1
	v_add_u32_e32 v50, 0x90, v138
	v_ashrrev_i32_e32 v51, 31, v50
	v_lshlrev_b64 v[56:57], 11, v[50:51]
	v_mad_i64_i32 v[50:51], s[22:23], v50, s63, v[140:141]
	v_lshl_add_u64 v[60:61], v[50:51], 0, v[136:137]
	v_lshl_add_u64 v[50:51], s[4:5], 0, v[56:57]
	v_lshl_add_u64 v[50:51], v[50:51], 0, v[136:137]
	s_waitcnt vmcnt(17)
	s_nop 1
	v_mov_b64_e32 v[52:53], v[220:221]
	v_mov_b64_e32 v[54:55], v[222:223]
	s_waitcnt vmcnt(16)
	s_nop 1
	v_mov_b64_e32 v[56:57], v[224:225]
	v_mov_b64_e32 v[58:59], v[226:227]
	v_lshlrev_b32_e32 v62, 16, v52
	v_and_b32_e32 v63, 0xffff0000, v52
	v_lshlrev_b32_e32 v64, 16, v56
	v_and_b32_e32 v65, 0xffff0000, v56
	v_lshlrev_b32_e32 v52, 16, v53
	v_and_b32_e32 v53, 0xffff0000, v53
	v_lshlrev_b32_e32 v56, 16, v57
	v_and_b32_e32 v57, 0xffff0000, v57
	v_pk_fma_f32 v[48:49], v[48:49], v[52:53], v[56:57]
	v_lshlrev_b32_e32 v52, 16, v54
	v_and_b32_e32 v53, 0xffff0000, v54
	v_lshlrev_b32_e32 v56, 16, v58
	v_and_b32_e32 v57, 0xffff0000, v58
	v_pk_fma_f32 v[52:53], v[42:43], v[52:53], v[56:57]
	v_lshlrev_b32_e32 v42, 16, v55
	v_and_b32_e32 v43, 0xffff0000, v55
	v_lshlrev_b32_e32 v54, 16, v59
	v_and_b32_e32 v55, 0xffff0000, v59
	v_pk_fma_f32 v[46:47], v[46:47], v[62:63], v[64:65]
	v_pk_fma_f32 v[54:55], v[44:45], v[42:43], v[54:55]
	v_cvt_pk_bf16_f32 v42, v46, v47
	v_cvt_pk_bf16_f32 v43, v48, v49
	v_cvt_pk_bf16_f32 v44, v52, v53
	v_cvt_pk_bf16_f32 v45, v54, v55
	global_store_dwordx4 v[50:51], v[42:45], off
	s_waitcnt vmcnt(15)
	s_nop 1
	v_mov_b64_e32 v[42:43], v[228:229]
	v_mov_b64_e32 v[44:45], v[230:231]
	s_nop 0
	s_waitcnt vmcnt(14)
	s_nop 1
	v_mov_b64_e32 v[46:47], v[232:233]
	v_mov_b64_e32 v[48:49], v[234:235]
	v_lshlrev_b32_e32 v52, 16, v42
	v_and_b32_e32 v53, 0xffff0000, v42
	v_lshlrev_b32_e32 v54, 16, v46
	v_and_b32_e32 v55, 0xffff0000, v46
	v_lshlrev_b32_e32 v42, 16, v43
	v_and_b32_e32 v43, 0xffff0000, v43
	v_lshlrev_b32_e32 v46, 16, v47
	v_and_b32_e32 v47, 0xffff0000, v47
	v_pk_fma_f32 v[40:41], v[40:41], v[42:43], v[46:47]
	v_lshlrev_b32_e32 v42, 16, v44
	v_and_b32_e32 v43, 0xffff0000, v44
	v_lshlrev_b32_e32 v46, 16, v48
	v_and_b32_e32 v47, 0xffff0000, v48
	v_pk_fma_f32 v[42:43], v[34:35], v[42:43], v[46:47]
	v_lshlrev_b32_e32 v34, 16, v45
	v_and_b32_e32 v35, 0xffff0000, v45
	v_lshlrev_b32_e32 v44, 16, v49
	v_and_b32_e32 v45, 0xffff0000, v49
	v_pk_fma_f32 v[38:39], v[38:39], v[52:53], v[54:55]
	v_pk_fma_f32 v[44:45], v[36:37], v[34:35], v[44:45]
	v_cvt_pk_bf16_f32 v34, v38, v39
	v_cvt_pk_bf16_f32 v35, v40, v41
	v_cvt_pk_bf16_f32 v36, v42, v43
	v_cvt_pk_bf16_f32 v37, v44, v45
	global_store_dwordx4 v[50:51], v[34:37], off offset:256
	s_nop 1
	v_add_u32_e32 v34, 0xa0, v138
	v_ashrrev_i32_e32 v35, 31, v34
	v_lshlrev_b64 v[40:41], 11, v[34:35]
	v_mad_i64_i32 v[34:35], s[22:23], v34, s63, v[140:141]
	v_lshl_add_u64 v[44:45], v[34:35], 0, v[136:137]
	v_lshl_add_u64 v[34:35], s[4:5], 0, v[40:41]
	v_lshl_add_u64 v[34:35], v[34:35], 0, v[136:137]
	s_waitcnt vmcnt(13)
	s_nop 1
	v_mov_b64_e32 v[36:37], v[236:237]
	v_mov_b64_e32 v[38:39], v[238:239]
	s_waitcnt vmcnt(12)
	s_nop 1
	v_mov_b64_e32 v[40:41], v[240:241]
	v_mov_b64_e32 v[42:43], v[242:243]
	v_lshlrev_b32_e32 v46, 16, v36
	v_and_b32_e32 v47, 0xffff0000, v36
	v_lshlrev_b32_e32 v48, 16, v40
	v_and_b32_e32 v49, 0xffff0000, v40
	v_lshlrev_b32_e32 v36, 16, v37
	v_and_b32_e32 v37, 0xffff0000, v37
	v_lshlrev_b32_e32 v40, 16, v41
	v_and_b32_e32 v41, 0xffff0000, v41
	v_pk_fma_f32 v[32:33], v[32:33], v[36:37], v[40:41]
	v_lshlrev_b32_e32 v36, 16, v38
	v_and_b32_e32 v37, 0xffff0000, v38
	v_lshlrev_b32_e32 v40, 16, v42
	v_and_b32_e32 v41, 0xffff0000, v42
	v_pk_fma_f32 v[36:37], v[26:27], v[36:37], v[40:41]
	v_lshlrev_b32_e32 v26, 16, v39
	v_and_b32_e32 v27, 0xffff0000, v39
	v_lshlrev_b32_e32 v38, 16, v43
	v_and_b32_e32 v39, 0xffff0000, v43
	v_pk_fma_f32 v[30:31], v[30:31], v[46:47], v[48:49]
	v_pk_fma_f32 v[38:39], v[28:29], v[26:27], v[38:39]
	v_cvt_pk_bf16_f32 v26, v30, v31
	v_cvt_pk_bf16_f32 v27, v32, v33
	v_cvt_pk_bf16_f32 v28, v36, v37
	v_cvt_pk_bf16_f32 v29, v38, v39
	global_store_dwordx4 v[34:35], v[26:29], off
	s_waitcnt vmcnt(11)
	s_nop 1
	v_mov_b64_e32 v[26:27], v[182:183]
	v_mov_b64_e32 v[28:29], v[184:185]
	s_nop 0
	s_waitcnt vmcnt(10)
	s_nop 1
	v_mov_b64_e32 v[30:31], v[186:187]
	v_mov_b64_e32 v[32:33], v[188:189]
	v_lshlrev_b32_e32 v36, 16, v26
	v_and_b32_e32 v37, 0xffff0000, v26
	v_lshlrev_b32_e32 v38, 16, v30
	v_and_b32_e32 v39, 0xffff0000, v30
	v_lshlrev_b32_e32 v26, 16, v27
	v_and_b32_e32 v27, 0xffff0000, v27
	v_lshlrev_b32_e32 v30, 16, v31
	v_and_b32_e32 v31, 0xffff0000, v31
	v_pk_fma_f32 v[24:25], v[24:25], v[26:27], v[30:31]
	v_lshlrev_b32_e32 v26, 16, v28
	v_and_b32_e32 v27, 0xffff0000, v28
	v_lshlrev_b32_e32 v30, 16, v32
	v_and_b32_e32 v31, 0xffff0000, v32
	v_pk_fma_f32 v[26:27], v[18:19], v[26:27], v[30:31]
	v_lshlrev_b32_e32 v18, 16, v29
	v_and_b32_e32 v19, 0xffff0000, v29
	v_lshlrev_b32_e32 v28, 16, v33
	v_and_b32_e32 v29, 0xffff0000, v33
	v_pk_fma_f32 v[22:23], v[22:23], v[36:37], v[38:39]
	v_pk_fma_f32 v[28:29], v[20:21], v[18:19], v[28:29]
	v_cvt_pk_bf16_f32 v18, v22, v23
	v_cvt_pk_bf16_f32 v19, v24, v25
	v_cvt_pk_bf16_f32 v20, v26, v27
	v_cvt_pk_bf16_f32 v21, v28, v29
	global_store_dwordx4 v[34:35], v[18:21], off offset:256
	s_nop 1
	v_add_u32_e32 v18, 0xb0, v138
	v_ashrrev_i32_e32 v19, 31, v18
	v_lshlrev_b64 v[24:25], 11, v[18:19]
	v_mad_i64_i32 v[18:19], s[22:23], v18, s63, v[140:141]
	v_lshl_add_u64 v[28:29], v[18:19], 0, v[136:137]
	v_lshl_add_u64 v[18:19], s[4:5], 0, v[24:25]
	v_lshl_add_u64 v[18:19], v[18:19], 0, v[136:137]
	s_waitcnt vmcnt(9)
	s_nop 1
	v_mov_b64_e32 v[20:21], v[204:205]
	v_mov_b64_e32 v[22:23], v[206:207]
	s_waitcnt vmcnt(8)
	s_nop 1
	v_mov_b64_e32 v[24:25], v[208:209]
	v_mov_b64_e32 v[26:27], v[210:211]
	s_mov_b64 s[22:23], -1
	v_lshlrev_b32_e32 v30, 16, v20
	v_and_b32_e32 v31, 0xffff0000, v20
	v_lshlrev_b32_e32 v32, 16, v24
	v_and_b32_e32 v33, 0xffff0000, v24
	v_lshlrev_b32_e32 v20, 16, v21
	v_and_b32_e32 v21, 0xffff0000, v21
	v_lshlrev_b32_e32 v24, 16, v25
	v_and_b32_e32 v25, 0xffff0000, v25
	v_pk_fma_f32 v[16:17], v[16:17], v[20:21], v[24:25]
	v_lshlrev_b32_e32 v20, 16, v22
	v_and_b32_e32 v21, 0xffff0000, v22
	v_lshlrev_b32_e32 v24, 16, v26
	v_and_b32_e32 v25, 0xffff0000, v26
	v_pk_fma_f32 v[20:21], v[10:11], v[20:21], v[24:25]
	v_lshlrev_b32_e32 v10, 16, v23
	v_and_b32_e32 v11, 0xffff0000, v23
	v_lshlrev_b32_e32 v22, 16, v27
	v_and_b32_e32 v23, 0xffff0000, v27
	v_pk_fma_f32 v[14:15], v[14:15], v[30:31], v[32:33]
	v_pk_fma_f32 v[22:23], v[12:13], v[10:11], v[22:23]
	v_cvt_pk_bf16_f32 v10, v14, v15
	v_cvt_pk_bf16_f32 v11, v16, v17
	v_cvt_pk_bf16_f32 v12, v20, v21
	v_cvt_pk_bf16_f32 v13, v22, v23
	global_store_dwordx4 v[18:19], v[10:13], off
	s_waitcnt vmcnt(7)
	s_nop 1
	v_mov_b64_e32 v[10:11], v[212:213]
	v_mov_b64_e32 v[12:13], v[214:215]
	s_nop 0
	s_waitcnt vmcnt(6)
	s_nop 1
	v_mov_b64_e32 v[14:15], v[216:217]
	v_mov_b64_e32 v[16:17], v[218:219]
	v_lshlrev_b32_e32 v20, 16, v10
	v_and_b32_e32 v21, 0xffff0000, v10
	v_lshlrev_b32_e32 v22, 16, v14
	v_and_b32_e32 v23, 0xffff0000, v14
	v_lshlrev_b32_e32 v10, 16, v11
	v_and_b32_e32 v11, 0xffff0000, v11
	v_lshlrev_b32_e32 v14, 16, v15
	v_and_b32_e32 v15, 0xffff0000, v15
	v_pk_fma_f32 v[8:9], v[8:9], v[10:11], v[14:15]
	v_lshlrev_b32_e32 v10, 16, v12
	v_and_b32_e32 v11, 0xffff0000, v12
	v_lshlrev_b32_e32 v14, 16, v16
	v_and_b32_e32 v15, 0xffff0000, v16
	v_pk_fma_f32 v[10:11], v[2:3], v[10:11], v[14:15]
	v_lshlrev_b32_e32 v2, 16, v13
	v_and_b32_e32 v3, 0xffff0000, v13
	v_lshlrev_b32_e32 v12, 16, v17
	v_and_b32_e32 v13, 0xffff0000, v17
	v_pk_fma_f32 v[6:7], v[6:7], v[20:21], v[22:23]
	v_pk_fma_f32 v[12:13], v[4:5], v[2:3], v[12:13]
	v_cvt_pk_bf16_f32 v2, v6, v7
	v_cvt_pk_bf16_f32 v3, v8, v9
	v_cvt_pk_bf16_f32 v4, v10, v11
	v_cvt_pk_bf16_f32 v5, v12, v13
	global_store_dwordx4 v[18:19], v[2:5], off offset:256
	s_cbranch_vccnz .LBB0_1438
	s_andn2_b64 vcc, exec, s[6:7]
	s_cbranch_vccnz .LBB0_1437
	s_barrier
	s_branch .LBB0_1437
